# attention QK/PV: LDS fragment reads software-pipelined 7-9 deep, vmcnt waits dropped from QK
# speedup vs baseline: 1.0110x; 1.0110x over previous
.LBB0_625:
	s_sub_i32 s73, s18, 63
	s_cmp_gt_i32 s73, s27
	s_cbranch_scc1 .LBB0_638
	s_bitcmp1_b32 s72, 0
	s_cselect_b32 s72, 0x2400, 0
	v_add_u32_e32 v32, s72, v188
	s_setprio 1
	ds_read_b128 v[214:217], v32
	ds_read_b128 v[218:221], v32 offset:4608
	ds_read_b128 v[222:225], v32 offset:32
	ds_read_b128 v[226:229], v32 offset:4640
	ds_read_b128 v[230:233], v32 offset:64
	ds_read_b128 v[234:237], v32 offset:4672
	ds_read_b128 v[238:241], v32 offset:96
	ds_read_b128 v[244:247], v32 offset:4704
	s_waitcnt lgkmcnt(7)
	v_mfma_f32_32x32x16_bf16 v[114:129], v[214:217], v[146:149], v[98:113]
	s_waitcnt lgkmcnt(6)
	v_mfma_f32_32x32x16_bf16 v[130:145], v[218:221], v[146:149], v[98:113]
	s_waitcnt lgkmcnt(5)
	v_mfma_f32_32x32x16_bf16 v[114:129], v[222:225], v[150:153], v[114:129]
	s_waitcnt lgkmcnt(4)
	v_mfma_f32_32x32x16_bf16 v[130:145], v[226:229], v[150:153], v[130:145]
	s_waitcnt lgkmcnt(3)
	v_mfma_f32_32x32x16_bf16 v[114:129], v[230:233], v[154:157], v[114:129]
	s_waitcnt lgkmcnt(2)
	v_mfma_f32_32x32x16_bf16 v[130:145], v[234:237], v[154:157], v[130:145]
	s_waitcnt lgkmcnt(1)
	v_mfma_f32_32x32x16_bf16 v[114:129], v[238:241], v[158:161], v[114:129]
	s_waitcnt lgkmcnt(0)
	v_mfma_f32_32x32x16_bf16 v[130:145], v[244:247], v[158:161], v[130:145]
	s_setprio 0
	s_cmp_le_i32 s18, s76
	s_cbranch_scc1 .LBB0_628
	v_add_u32_e32 v32, s18, v190
	v_subrev_u32_e32 v200, 31, v32
	v_subrev_u32_e32 v198, 63, v32
	v_cmp_le_i32_e32 vcc, v200, v166
	s_nop 4
	v_cndmask_b32_e32 v130, v208, v130, vcc
	v_cmp_lt_i32_e32 vcc, v198, v166
	s_nop 1
	v_cndmask_b32_e32 v115, v208, v115, vcc
	v_cmp_le_i32_e32 vcc, v198, v166
	v_subrev_u32_e32 v198, 30, v32
	s_nop 0
	v_cndmask_b32_e32 v114, v208, v114, vcc
	v_cmp_le_i32_e32 vcc, v198, v166
	v_subrev_u32_e32 v198, 61, v32
	s_nop 0
	v_cndmask_b32_e32 v131, v208, v131, vcc
	v_cmp_le_i32_e32 vcc, v198, v166
	v_subrev_u32_e32 v198, 29, v32
	s_nop 0
	v_cndmask_b32_e32 v116, v208, v116, vcc
	v_cmp_le_i32_e32 vcc, v198, v166
	v_subrev_u32_e32 v198, 60, v32
	s_nop 0
	v_cndmask_b32_e32 v132, v208, v132, vcc
	v_cmp_le_i32_e32 vcc, v198, v166
	v_subrev_u32_e32 v198, 28, v32
	s_nop 0
	v_cndmask_b32_e32 v117, v208, v117, vcc
	v_cmp_le_i32_e32 vcc, v198, v166
	v_subrev_u32_e32 v198, 55, v32
	s_nop 0
	v_cndmask_b32_e32 v133, v208, v133, vcc
	v_cmp_le_i32_e32 vcc, v198, v166
	v_subrev_u32_e32 v198, 23, v32
	s_nop 0
	v_cndmask_b32_e32 v118, v208, v118, vcc
	v_cmp_le_i32_e32 vcc, v198, v166
	v_subrev_u32_e32 v198, 54, v32
	s_nop 0
	v_cndmask_b32_e32 v134, v208, v134, vcc
	v_cmp_le_i32_e32 vcc, v198, v166
	v_subrev_u32_e32 v198, 22, v32
	s_nop 0
	v_cndmask_b32_e32 v119, v208, v119, vcc
	v_cmp_le_i32_e32 vcc, v198, v166
	v_subrev_u32_e32 v198, 53, v32
	s_nop 0
	v_cndmask_b32_e32 v135, v208, v135, vcc
	v_cmp_le_i32_e32 vcc, v198, v166
	v_subrev_u32_e32 v198, 21, v32
	s_nop 0
	v_cndmask_b32_e32 v120, v208, v120, vcc
	v_cmp_le_i32_e32 vcc, v198, v166
	v_subrev_u32_e32 v198, 52, v32
	s_nop 0
	v_cndmask_b32_e32 v136, v208, v136, vcc
	v_cmp_le_i32_e32 vcc, v198, v166
	v_subrev_u32_e32 v198, 20, v32
	s_nop 0
	v_cndmask_b32_e32 v121, v208, v121, vcc
	v_cmp_le_i32_e32 vcc, v198, v166
	v_subrev_u32_e32 v198, 47, v32
	s_nop 0
	v_cndmask_b32_e32 v137, v208, v137, vcc
	v_cmp_le_i32_e32 vcc, v198, v166
	v_add_u32_e32 v198, -15, v32
	s_nop 0
	v_cndmask_b32_e32 v122, v208, v122, vcc
	v_cmp_le_i32_e32 vcc, v198, v166
	v_subrev_u32_e32 v198, 46, v32
	s_nop 0
	v_cndmask_b32_e32 v138, v208, v138, vcc
	v_cmp_le_i32_e32 vcc, v198, v166
	v_add_u32_e32 v198, -14, v32
	s_nop 0
	v_cndmask_b32_e32 v123, v208, v123, vcc
	v_cmp_le_i32_e32 vcc, v198, v166
	v_subrev_u32_e32 v198, 45, v32
	s_nop 0
	v_cndmask_b32_e32 v139, v208, v139, vcc
	v_cmp_le_i32_e32 vcc, v198, v166
	v_add_u32_e32 v198, -13, v32
	s_nop 0
	v_cndmask_b32_e32 v124, v208, v124, vcc
	v_cmp_le_i32_e32 vcc, v198, v166
	v_subrev_u32_e32 v198, 44, v32
	s_nop 0
	v_cndmask_b32_e32 v140, v208, v140, vcc
	v_cmp_le_i32_e32 vcc, v198, v166
	v_add_u32_e32 v198, -12, v32
	s_nop 0
	v_cndmask_b32_e32 v125, v208, v125, vcc
	v_cmp_le_i32_e32 vcc, v198, v166
	v_subrev_u32_e32 v198, 39, v32
	s_nop 0
	v_cndmask_b32_e32 v141, v208, v141, vcc
	v_cmp_le_i32_e32 vcc, v198, v166
	v_add_u32_e32 v198, -7, v32
	s_nop 0
	v_cndmask_b32_e32 v126, v208, v126, vcc
	v_cmp_le_i32_e32 vcc, v198, v166
	v_subrev_u32_e32 v198, 38, v32
	s_nop 0
	v_cndmask_b32_e32 v142, v208, v142, vcc
	v_cmp_le_i32_e32 vcc, v198, v166
	v_add_u32_e32 v198, -6, v32
	s_nop 0
	v_cndmask_b32_e32 v127, v208, v127, vcc
	v_cmp_le_i32_e32 vcc, v198, v166
	v_subrev_u32_e32 v198, 37, v32
	s_nop 0
	v_cndmask_b32_e32 v143, v208, v143, vcc
	v_cmp_le_i32_e32 vcc, v198, v166
	v_add_u32_e32 v198, -5, v32
	s_nop 0
	v_cndmask_b32_e32 v128, v208, v128, vcc
	v_cmp_le_i32_e32 vcc, v198, v166
	v_subrev_u32_e32 v198, 36, v32
	v_add_u32_e32 v32, -4, v32
	v_cndmask_b32_e32 v144, v208, v144, vcc
	v_cmp_le_i32_e32 vcc, v198, v166
	s_nop 1
	v_cndmask_b32_e32 v129, v208, v129, vcc
	v_cmp_le_i32_e32 vcc, v32, v166
	s_nop 1
	v_cndmask_b32_e32 v145, v208, v145, vcc

.LBB0_637:
	v_exp_f32_e32 v198, v114
	v_exp_f32_e32 v200, v130
	v_exp_f32_e32 v32, v115
	v_exp_f32_e32 v114, v131
	v_exp_f32_e32 v212, v132
	v_add_f32_e32 v115, v200, v198
	v_exp_f32_e32 v122, v122
	v_pk_add_f32 v[130:131], v[114:115], v[32:33]
	v_exp_f32_e32 v115, v116
	v_pk_add_f32 v[130:131], v[130:131], v[130:131] op_sel_hi:[0,1]
	v_exp_f32_e32 v130, v117
	v_exp_f32_e32 v116, v133
	v_add_f32_e32 v117, v212, v115
	s_mulk_i32 s24, 0x5000
	v_pk_add_f32 v[132:133], v[116:117], v[130:131]
	s_nop 0
	v_pk_add_f32 v[132:133], v[132:133], v[132:133] op_sel_hi:[0,1]
	v_exp_f32_e32 v117, v118
	v_exp_f32_e32 v131, v134
	v_exp_f32_e32 v132, v119
	v_exp_f32_e32 v134, v135
	v_add_f32_e32 v135, v131, v117
	v_pk_add_f32 v[118:119], v[134:135], v[132:133]
	s_nop 0
	v_pk_add_f32 v[202:203], v[118:119], v[118:119] op_sel_hi:[0,1]
	v_exp_f32_e32 v133, v120
	v_exp_f32_e32 v135, v136
	v_exp_f32_e32 v202, v121
	v_exp_f32_e32 v136, v137
	v_add_f32_e32 v137, v135, v133
	v_pk_add_f32 v[118:119], v[136:137], v[202:203]
	s_nop 0
	v_pk_add_f32 v[120:121], v[118:119], v[118:119] op_sel_hi:[0,1]
	v_exp_f32_e32 v137, v138
	v_exp_f32_e32 v120, v123
	v_exp_f32_e32 v138, v139
	v_exp_f32_e32 v203, v142
	v_add_f32_e32 v139, v137, v122
	v_exp_f32_e32 v142, v143
	v_pk_add_f32 v[118:119], v[138:139], v[120:121]
	v_exp_f32_e32 v121, v124
	v_pk_add_f32 v[204:205], v[118:119], v[118:119] op_sel_hi:[0,1]
	v_exp_f32_e32 v139, v140
	v_exp_f32_e32 v204, v125
	v_exp_f32_e32 v124, v141
	v_cvt_pk_bf16_f32 v122, v122, v120
	v_add_f32_e32 v125, v139, v121
	v_cvt_pk_bf16_f32 v123, v121, v204
	v_pk_add_f32 v[118:119], v[124:125], v[204:205]
	v_exp_f32_e32 v125, v126
	v_pk_add_f32 v[140:141], v[118:119], v[118:119] op_sel_hi:[0,1]
	v_exp_f32_e32 v140, v127
	v_cvt_pk_bf16_f32 v126, v200, v114
	v_add_f32_e32 v143, v203, v125
	v_cvt_pk_bf16_f32 v114, v137, v138
	v_pk_add_f32 v[118:119], v[142:143], v[140:141]
	v_exp_f32_e32 v141, v128
	v_pk_add_f32 v[210:211], v[118:119], v[118:119] op_sel_hi:[0,1]
	v_exp_f32_e32 v143, v144
	v_exp_f32_e32 v210, v129
	v_exp_f32_e32 v144, v145
	v_cvt_pk_bf16_f32 v127, v212, v116
	v_add_f32_e32 v145, v143, v141
	v_cvt_pk_bf16_f32 v120, v117, v132
	v_pk_add_f32 v[118:119], v[144:145], v[210:211]
	v_cvt_pk_bf16_f32 v128, v131, v134
	v_add_f32_e32 v145, v118, v119
	v_cvt_pk_bf16_f32 v118, v198, v32
	v_cvt_pk_bf16_f32 v119, v115, v130
	v_cvt_pk_bf16_f32 v115, v139, v124
	v_cvt_pk_bf16_f32 v124, v125, v140
	v_cvt_pk_bf16_f32 v116, v203, v142
	v_cvt_pk_bf16_f32 v121, v133, v202
	v_cvt_pk_bf16_f32 v125, v141, v210
	v_cvt_pk_bf16_f32 v129, v135, v136
	v_cvt_pk_bf16_f32 v117, v143, v144
	v_add_u32_e32 v32, s24, v194
	s_setprio 1
	ds_read_b64_tr_b16 v[214:215], v32 offset:18432
	ds_read_b64_tr_b16 v[216:217], v32 offset:20992
	ds_read_b64_tr_b16 v[218:219], v32 offset:18496
	ds_read_b64_tr_b16 v[220:221], v32 offset:21056
	ds_read_b64_tr_b16 v[222:223], v32 offset:18560
	ds_read_b64_tr_b16 v[224:225], v32 offset:21120
	ds_read_b64_tr_b16 v[226:227], v32 offset:18624
	ds_read_b64_tr_b16 v[228:229], v32 offset:21184
	ds_read_b64_tr_b16 v[230:231], v32 offset:23552
	ds_read_b64_tr_b16 v[232:233], v32 offset:26112
	ds_read_b64_tr_b16 v[234:235], v32 offset:23616
	ds_read_b64_tr_b16 v[236:237], v32 offset:26176
	ds_read_b64_tr_b16 v[238:239], v32 offset:23680
	ds_read_b64_tr_b16 v[240:241], v32 offset:26240
	s_waitcnt lgkmcnt(12)
	v_mfma_f32_32x32x16_bf16 v[82:97], v[118:121], v[214:217], v[82:97]
	v_add_f32_e32 v182, v182, v145
	ds_read_b64_tr_b16 v[214:215], v32 offset:23744
	ds_read_b64_tr_b16 v[216:217], v32 offset:26304
	s_waitcnt lgkmcnt(12)
	v_mfma_f32_32x32x16_bf16 v[66:81], v[118:121], v[218:221], v[66:81]
	ds_read_b64_tr_b16 v[218:219], v32 offset:28672
	ds_read_b64_tr_b16 v[220:221], v32 offset:31232
	s_waitcnt lgkmcnt(12)
	v_mfma_f32_32x32x16_bf16 v[50:65], v[118:121], v[222:225], v[50:65]
	ds_read_b64_tr_b16 v[222:223], v32 offset:28736
	ds_read_b64_tr_b16 v[224:225], v32 offset:31296
	s_waitcnt lgkmcnt(12)
	v_mfma_f32_32x32x16_bf16 v[34:49], v[118:121], v[226:229], v[34:49]
	ds_read_b64_tr_b16 v[226:227], v32 offset:28800
	ds_read_b64_tr_b16 v[228:229], v32 offset:31360
	s_waitcnt lgkmcnt(12)
	v_mfma_f32_32x32x16_bf16 v[82:97], v[122:125], v[230:233], v[82:97]
	ds_read_b64_tr_b16 v[230:231], v32 offset:28864
	ds_read_b64_tr_b16 v[232:233], v32 offset:31424
	s_waitcnt lgkmcnt(12)
	v_mfma_f32_32x32x16_bf16 v[66:81], v[122:125], v[234:237], v[66:81]
	ds_read_b64_tr_b16 v[234:235], v32 offset:33792
	ds_read_b64_tr_b16 v[236:237], v32 offset:36352
	s_waitcnt lgkmcnt(12)
	v_mfma_f32_32x32x16_bf16 v[50:65], v[122:125], v[238:241], v[50:65]
	ds_read_b64_tr_b16 v[238:239], v32 offset:33856
	ds_read_b64_tr_b16 v[240:241], v32 offset:36416
	s_waitcnt lgkmcnt(12)
	v_mfma_f32_32x32x16_bf16 v[34:49], v[122:125], v[214:217], v[34:49]
	ds_read_b64_tr_b16 v[214:215], v32 offset:33920
	ds_read_b64_tr_b16 v[216:217], v32 offset:36480
	s_waitcnt lgkmcnt(12)
	v_mfma_f32_32x32x16_bf16 v[82:97], v[126:129], v[218:221], v[82:97]
	ds_read_b64_tr_b16 v[218:219], v32 offset:33984
	ds_read_b64_tr_b16 v[220:221], v32 offset:36544
	s_waitcnt lgkmcnt(12)
	v_mfma_f32_32x32x16_bf16 v[66:81], v[126:129], v[222:225], v[66:81]
	s_waitcnt lgkmcnt(10)
	v_mfma_f32_32x32x16_bf16 v[50:65], v[126:129], v[226:229], v[50:65]
	s_waitcnt lgkmcnt(8)
	v_mfma_f32_32x32x16_bf16 v[34:49], v[126:129], v[230:233], v[34:49]
	s_waitcnt lgkmcnt(6)
	v_mfma_f32_32x32x16_bf16 v[82:97], v[114:117], v[234:237], v[82:97]
	s_waitcnt lgkmcnt(4)
	v_mfma_f32_32x32x16_bf16 v[66:81], v[114:117], v[238:241], v[66:81]
	s_waitcnt lgkmcnt(2)
	v_mfma_f32_32x32x16_bf16 v[50:65], v[114:117], v[214:217], v[50:65]
	s_waitcnt lgkmcnt(0)
	v_mfma_f32_32x32x16_bf16 v[34:49], v[114:117], v[218:221], v[34:49]
	s_setprio 0

; template <int DQK>
; __device__ __forceinline__ void attn_pass4(LAS unsigned char* lds, const bf16* Qp, int qpitch, const bf16* Kp, int kpitch, const bf16* Vp, int vpitch, int q0, f32x16 (&o)[4], float (&rl)[16]) {
;     ...
;             if (t > 0 && ATT_VIS(t - 1)) ATT_B(vprev);
.LBB0_651:
	s_cmp_lg_u32 s18, 0
	s_cselect_b64 s[72:73], -1, 0
	s_cmp_eq_u32 s18, 0
	s_mov_b32 s10, 0
	s_cbranch_scc1 .LBB0_655
	s_sub_i32 s10, s2, 64
	s_cmp_gt_i32 s10, s74
	s_cbranch_scc1 .LBB0_654
	s_mulk_i32 s24, 0x5000
	v_add_u32_e32 v32, s24, v177
	s_setprio 1
	ds_read_b64_tr_b16 v[214:215], v32 offset:18432
	ds_read_b64_tr_b16 v[216:217], v32 offset:20992
	ds_read_b64_tr_b16 v[218:219], v32 offset:18496
	ds_read_b64_tr_b16 v[220:221], v32 offset:21056
	ds_read_b64_tr_b16 v[222:223], v32 offset:18560
	ds_read_b64_tr_b16 v[224:225], v32 offset:21120
	ds_read_b64_tr_b16 v[226:227], v32 offset:18624
	ds_read_b64_tr_b16 v[228:229], v32 offset:21184
	ds_read_b64_tr_b16 v[230:231], v32 offset:23552
	ds_read_b64_tr_b16 v[232:233], v32 offset:26112
	ds_read_b64_tr_b16 v[234:235], v32 offset:23616
	ds_read_b64_tr_b16 v[236:237], v32 offset:26176
	ds_read_b64_tr_b16 v[238:239], v32 offset:23680
	ds_read_b64_tr_b16 v[240:241], v32 offset:26240
	s_waitcnt lgkmcnt(12)
	v_mfma_f32_32x32x16_bf16 v[82:97], v[126:129], v[214:217], v[82:97]
	ds_read_b64_tr_b16 v[214:215], v32 offset:23744
	ds_read_b64_tr_b16 v[216:217], v32 offset:26304
	s_waitcnt lgkmcnt(12)
	v_mfma_f32_32x32x16_bf16 v[66:81], v[126:129], v[218:221], v[66:81]
	ds_read_b64_tr_b16 v[218:219], v32 offset:28672
	ds_read_b64_tr_b16 v[220:221], v32 offset:31232
	s_waitcnt lgkmcnt(12)
	v_mfma_f32_32x32x16_bf16 v[50:65], v[126:129], v[222:225], v[50:65]
	ds_read_b64_tr_b16 v[222:223], v32 offset:28736
	ds_read_b64_tr_b16 v[224:225], v32 offset:31296
	s_waitcnt lgkmcnt(12)
	v_mfma_f32_32x32x16_bf16 v[34:49], v[126:129], v[226:229], v[34:49]
	ds_read_b64_tr_b16 v[226:227], v32 offset:28800
	ds_read_b64_tr_b16 v[228:229], v32 offset:31360
	s_waitcnt lgkmcnt(12)
	v_mfma_f32_32x32x16_bf16 v[82:97], v[122:125], v[230:233], v[82:97]
	ds_read_b64_tr_b16 v[230:231], v32 offset:28864
	ds_read_b64_tr_b16 v[232:233], v32 offset:31424
	s_waitcnt lgkmcnt(12)
	v_mfma_f32_32x32x16_bf16 v[66:81], v[122:125], v[234:237], v[66:81]
	ds_read_b64_tr_b16 v[234:235], v32 offset:33792
	ds_read_b64_tr_b16 v[236:237], v32 offset:36352
	s_waitcnt lgkmcnt(12)
	v_mfma_f32_32x32x16_bf16 v[50:65], v[122:125], v[238:241], v[50:65]
	ds_read_b64_tr_b16 v[238:239], v32 offset:33856
	ds_read_b64_tr_b16 v[240:241], v32 offset:36416
	s_waitcnt lgkmcnt(12)
	v_mfma_f32_32x32x16_bf16 v[34:49], v[122:125], v[214:217], v[34:49]
	ds_read_b64_tr_b16 v[214:215], v32 offset:33920
	ds_read_b64_tr_b16 v[216:217], v32 offset:36480
	s_waitcnt lgkmcnt(12)
	v_mfma_f32_32x32x16_bf16 v[82:97], v[118:121], v[218:221], v[82:97]
	ds_read_b64_tr_b16 v[218:219], v32 offset:33984
	ds_read_b64_tr_b16 v[220:221], v32 offset:36544
	s_waitcnt lgkmcnt(12)
	v_mfma_f32_32x32x16_bf16 v[66:81], v[118:121], v[222:225], v[66:81]
	s_waitcnt lgkmcnt(10)
	v_mfma_f32_32x32x16_bf16 v[50:65], v[118:121], v[226:229], v[50:65]
	s_waitcnt lgkmcnt(8)
	v_mfma_f32_32x32x16_bf16 v[34:49], v[118:121], v[230:233], v[34:49]
	s_waitcnt lgkmcnt(6)
	v_mfma_f32_32x32x16_bf16 v[82:97], v[114:117], v[234:237], v[82:97]
	s_waitcnt lgkmcnt(4)
	v_mfma_f32_32x32x16_bf16 v[66:81], v[114:117], v[238:241], v[66:81]
	s_waitcnt lgkmcnt(2)
	v_mfma_f32_32x32x16_bf16 v[50:65], v[114:117], v[214:217], v[50:65]
	s_waitcnt lgkmcnt(0)
	v_mfma_f32_32x32x16_bf16 v[34:49], v[114:117], v[218:221], v[34:49]
	s_setprio 0

; template <int DQK>
; __device__ __forceinline__ void attn_pass4(LAS unsigned char* lds, const bf16* Qp, int qpitch, const bf16* Kp, int kpitch, const bf16* Vp, int vpitch, int q0, f32x16 (&o)[4], float (&rl)[16]) {
;     ...
;             if (ATT_VIS(t)) ATT_A(t);
.LBB0_655:
	s_cmp_gt_i32 s10, s74
	s_cbranch_scc1 .LBB0_669
	s_bitcmp1_b32 s18, 0
	s_cselect_b32 s11, 0x2400, 0
	v_add_u32_e32 v32, s11, v188
	s_setprio 1
	ds_read_b128 v[214:217], v32
	ds_read_b128 v[218:221], v32 offset:4608
	ds_read_b128 v[222:225], v32 offset:32
	ds_read_b128 v[226:229], v32 offset:4640
	ds_read_b128 v[230:233], v32 offset:64
	ds_read_b128 v[234:237], v32 offset:4672
	ds_read_b128 v[238:241], v32 offset:96
	ds_read_b128 v[244:247], v32 offset:4704
	s_waitcnt lgkmcnt(7)
	v_mfma_f32_32x32x16_bf16 v[114:129], v[214:217], v[146:149], v[98:113]
	s_waitcnt lgkmcnt(6)
	v_mfma_f32_32x32x16_bf16 v[130:145], v[218:221], v[146:149], v[98:113]
	s_waitcnt lgkmcnt(5)
	v_mfma_f32_32x32x16_bf16 v[114:129], v[222:225], v[150:153], v[114:129]
	s_waitcnt lgkmcnt(4)
	v_mfma_f32_32x32x16_bf16 v[130:145], v[226:229], v[150:153], v[130:145]
	s_waitcnt lgkmcnt(3)
	v_mfma_f32_32x32x16_bf16 v[114:129], v[230:233], v[154:157], v[114:129]
	s_waitcnt lgkmcnt(2)
	v_mfma_f32_32x32x16_bf16 v[130:145], v[234:237], v[154:157], v[130:145]
	s_waitcnt lgkmcnt(1)
	v_mfma_f32_32x32x16_bf16 v[114:129], v[238:241], v[158:161], v[114:129]
	s_waitcnt lgkmcnt(0)
	v_mfma_f32_32x32x16_bf16 v[130:145], v[244:247], v[158:161], v[130:145]
	s_setprio 0
	s_or_b32 s11, s10, 63
	s_cmp_le_i32 s11, s76
	s_cbranch_scc1 .LBB0_658
	v_or_b32_e32 v32, s10, v190
	v_or_b32_e32 v179, 32, v32
	v_cmp_le_i32_e32 vcc, v179, v166
	v_or_b32_e32 v179, 33, v32
	s_nop 3
	v_cndmask_b32_e32 v130, v208, v130, vcc
	v_cmp_lt_i32_e32 vcc, v32, v166
	s_nop 1
	v_cndmask_b32_e32 v115, v208, v115, vcc
	v_cmp_le_i32_e32 vcc, v32, v166
	s_nop 1
	v_cndmask_b32_e32 v114, v208, v114, vcc
	v_cmp_le_i32_e32 vcc, v179, v166
	v_or_b32_e32 v179, 2, v32
	s_nop 0
	v_cndmask_b32_e32 v131, v208, v131, vcc
	v_cmp_le_i32_e32 vcc, v179, v166
	v_or_b32_e32 v179, 34, v32
	s_nop 0
	v_cndmask_b32_e32 v116, v208, v116, vcc
	v_cmp_le_i32_e32 vcc, v179, v166
	v_or_b32_e32 v179, 3, v32
	s_nop 0
	v_cndmask_b32_e32 v132, v208, v132, vcc
	v_cmp_le_i32_e32 vcc, v179, v166
	v_or_b32_e32 v179, 35, v32
	s_nop 0
	v_cndmask_b32_e32 v117, v208, v117, vcc
	v_cmp_le_i32_e32 vcc, v179, v166
	v_or_b32_e32 v179, 8, v32
	s_nop 0
	v_cndmask_b32_e32 v133, v208, v133, vcc
	v_cmp_le_i32_e32 vcc, v179, v166
	v_or_b32_e32 v179, 40, v32
	s_nop 0
	v_cndmask_b32_e32 v118, v208, v118, vcc
	v_cmp_le_i32_e32 vcc, v179, v166
	v_or_b32_e32 v179, 9, v32
	s_nop 0
	v_cndmask_b32_e32 v134, v208, v134, vcc
	v_cmp_le_i32_e32 vcc, v179, v166
	v_or_b32_e32 v179, 41, v32
	s_nop 0
	v_cndmask_b32_e32 v119, v208, v119, vcc
	v_cmp_le_i32_e32 vcc, v179, v166
	v_or_b32_e32 v179, 10, v32
	s_nop 0
	v_cndmask_b32_e32 v135, v208, v135, vcc
	v_cmp_le_i32_e32 vcc, v179, v166
	v_or_b32_e32 v179, 42, v32
	s_nop 0
	v_cndmask_b32_e32 v120, v208, v120, vcc
	v_cmp_le_i32_e32 vcc, v179, v166
	v_or_b32_e32 v179, 11, v32
	s_nop 0
	v_cndmask_b32_e32 v136, v208, v136, vcc
	v_cmp_le_i32_e32 vcc, v179, v166
	v_or_b32_e32 v179, 43, v32
	s_nop 0
	v_cndmask_b32_e32 v121, v208, v121, vcc
	v_cmp_le_i32_e32 vcc, v179, v166
	v_or_b32_e32 v179, 16, v32
	s_nop 0
	v_cndmask_b32_e32 v137, v208, v137, vcc
	v_cmp_le_i32_e32 vcc, v179, v166
	v_or_b32_e32 v179, 48, v32
	s_nop 0
	v_cndmask_b32_e32 v122, v208, v122, vcc
	v_cmp_le_i32_e32 vcc, v179, v166
	v_or_b32_e32 v179, 17, v32
	s_nop 0
	v_cndmask_b32_e32 v138, v208, v138, vcc
	v_cmp_le_i32_e32 vcc, v179, v166
	v_or_b32_e32 v179, 49, v32
	s_nop 0
	v_cndmask_b32_e32 v123, v208, v123, vcc
	v_cmp_le_i32_e32 vcc, v179, v166
	v_or_b32_e32 v179, 18, v32
	s_nop 0
	v_cndmask_b32_e32 v139, v208, v139, vcc
	v_cmp_le_i32_e32 vcc, v179, v166
	v_or_b32_e32 v179, 50, v32
	s_nop 0
	v_cndmask_b32_e32 v124, v208, v124, vcc
	v_cmp_le_i32_e32 vcc, v179, v166
	v_or_b32_e32 v179, 19, v32
	s_nop 0
	v_cndmask_b32_e32 v140, v208, v140, vcc
	v_cmp_le_i32_e32 vcc, v179, v166
	v_or_b32_e32 v179, 51, v32
	s_nop 0
	v_cndmask_b32_e32 v125, v208, v125, vcc
	v_cmp_le_i32_e32 vcc, v179, v166
	v_or_b32_e32 v179, 24, v32
	s_nop 0
	v_cndmask_b32_e32 v141, v208, v141, vcc
	v_cmp_le_i32_e32 vcc, v179, v166
	v_or_b32_e32 v179, 56, v32
	s_nop 0
	v_cndmask_b32_e32 v126, v208, v126, vcc
	v_cmp_le_i32_e32 vcc, v179, v166
	v_or_b32_e32 v179, 25, v32
	s_nop 0
	v_cndmask_b32_e32 v142, v208, v142, vcc
	v_cmp_le_i32_e32 vcc, v179, v166
	v_or_b32_e32 v179, 57, v32
	s_nop 0
	v_cndmask_b32_e32 v127, v208, v127, vcc
	v_cmp_le_i32_e32 vcc, v179, v166
	v_or_b32_e32 v179, 26, v32
	s_nop 0
	v_cndmask_b32_e32 v143, v208, v143, vcc
	v_cmp_le_i32_e32 vcc, v179, v166
	v_or_b32_e32 v179, 58, v32
	s_nop 0
	v_cndmask_b32_e32 v128, v208, v128, vcc
	v_cmp_le_i32_e32 vcc, v179, v166
	v_or_b32_e32 v179, 27, v32
	v_or_b32_e32 v32, 59, v32
	v_cndmask_b32_e32 v144, v208, v144, vcc
	v_cmp_le_i32_e32 vcc, v179, v166
	s_nop 1
	v_cndmask_b32_e32 v129, v208, v129, vcc
	v_cmp_le_i32_e32 vcc, v32, v166
	s_nop 1
	v_cndmask_b32_e32 v145, v208, v145, vcc

; template <int DQK>
; __device__ __forceinline__ void attn_pass4(LAS unsigned char* lds, const bf16* Qp, int qpitch, const bf16* Kp, int kpitch, const bf16* Vp, int vpitch, int q0, f32x16 (&o)[4], float (&rl)[16]) {
;     ...
;         if (ATT_VIS(NT - 1)) ATT_B(vprev);
.LBB0_671:
	s_cmp_gt_i32 s3, 5
	s_cbranch_scc0 .LBB0_673
	s_mul_i32 s2, s5, 0x5000
	s_add_i32 s2, s2, 0
	v_add_u32_e32 v32, s2, v176
	v_add3_u32 v32, v32, v184, v186
	s_setprio 1
	ds_read_b64_tr_b16 v[214:215], v32 offset:18432
	ds_read_b64_tr_b16 v[216:217], v32 offset:20992
	ds_read_b64_tr_b16 v[218:219], v32 offset:18496
	ds_read_b64_tr_b16 v[220:221], v32 offset:21056
	ds_read_b64_tr_b16 v[222:223], v32 offset:18560
	ds_read_b64_tr_b16 v[224:225], v32 offset:21120
	ds_read_b64_tr_b16 v[226:227], v32 offset:18624
	ds_read_b64_tr_b16 v[228:229], v32 offset:21184
	ds_read_b64_tr_b16 v[230:231], v32 offset:23552
	ds_read_b64_tr_b16 v[232:233], v32 offset:26112
	ds_read_b64_tr_b16 v[234:235], v32 offset:23616
	ds_read_b64_tr_b16 v[236:237], v32 offset:26176
	ds_read_b64_tr_b16 v[238:239], v32 offset:23680
	ds_read_b64_tr_b16 v[240:241], v32 offset:26240
	s_waitcnt lgkmcnt(12)
	v_mfma_f32_32x32x16_bf16 v[82:97], v[126:129], v[214:217], v[82:97]
	ds_read_b64_tr_b16 v[214:215], v32 offset:23744
	ds_read_b64_tr_b16 v[216:217], v32 offset:26304
	s_waitcnt lgkmcnt(12)
	v_mfma_f32_32x32x16_bf16 v[66:81], v[126:129], v[218:221], v[66:81]
	ds_read_b64_tr_b16 v[218:219], v32 offset:28672
	ds_read_b64_tr_b16 v[220:221], v32 offset:31232
	s_waitcnt lgkmcnt(12)
	v_mfma_f32_32x32x16_bf16 v[50:65], v[126:129], v[222:225], v[50:65]
	ds_read_b64_tr_b16 v[222:223], v32 offset:28736
	ds_read_b64_tr_b16 v[224:225], v32 offset:31296
	s_waitcnt lgkmcnt(12)
	v_mfma_f32_32x32x16_bf16 v[34:49], v[126:129], v[226:229], v[34:49]
	ds_read_b64_tr_b16 v[226:227], v32 offset:28800
	ds_read_b64_tr_b16 v[228:229], v32 offset:31360
	s_waitcnt lgkmcnt(12)
	v_mfma_f32_32x32x16_bf16 v[82:97], v[122:125], v[230:233], v[82:97]
	ds_read_b64_tr_b16 v[230:231], v32 offset:28864
	ds_read_b64_tr_b16 v[232:233], v32 offset:31424
	s_waitcnt lgkmcnt(12)
	v_mfma_f32_32x32x16_bf16 v[66:81], v[122:125], v[234:237], v[66:81]
	ds_read_b64_tr_b16 v[234:235], v32 offset:33792
	ds_read_b64_tr_b16 v[236:237], v32 offset:36352
	s_waitcnt lgkmcnt(12)
	v_mfma_f32_32x32x16_bf16 v[50:65], v[122:125], v[238:241], v[50:65]
	ds_read_b64_tr_b16 v[238:239], v32 offset:33856
	ds_read_b64_tr_b16 v[240:241], v32 offset:36416
	s_waitcnt lgkmcnt(12)
	v_mfma_f32_32x32x16_bf16 v[34:49], v[122:125], v[214:217], v[34:49]
	ds_read_b64_tr_b16 v[214:215], v32 offset:33920
	ds_read_b64_tr_b16 v[216:217], v32 offset:36480
	s_waitcnt lgkmcnt(12)
	v_mfma_f32_32x32x16_bf16 v[82:97], v[118:121], v[218:221], v[82:97]
	ds_read_b64_tr_b16 v[218:219], v32 offset:33984
	ds_read_b64_tr_b16 v[220:221], v32 offset:36544
	s_waitcnt lgkmcnt(12)
	v_mfma_f32_32x32x16_bf16 v[66:81], v[118:121], v[222:225], v[66:81]
	s_waitcnt lgkmcnt(10)
	v_mfma_f32_32x32x16_bf16 v[50:65], v[118:121], v[226:229], v[50:65]
	s_waitcnt lgkmcnt(8)
	v_mfma_f32_32x32x16_bf16 v[34:49], v[118:121], v[230:233], v[34:49]
	s_waitcnt lgkmcnt(6)
	v_mfma_f32_32x32x16_bf16 v[82:97], v[114:117], v[234:237], v[82:97]
	s_waitcnt lgkmcnt(4)
	v_mfma_f32_32x32x16_bf16 v[66:81], v[114:117], v[238:241], v[66:81]
	s_waitcnt lgkmcnt(2)
	v_mfma_f32_32x32x16_bf16 v[50:65], v[114:117], v[214:217], v[50:65]
	s_waitcnt lgkmcnt(0)
	v_mfma_f32_32x32x16_bf16 v[34:49], v[114:117], v[218:221], v[34:49]
	s_setprio 0

.LBB0_825:
	s_sub_i32 s73, s18, 63
	s_cmp_gt_i32 s73, s26
	s_cbranch_scc1 .LBB0_838
	s_bitcmp1_b32 s72, 0
	s_cselect_b32 s72, 0x2400, 0
	v_add_u32_e32 v32, s72, v188
	s_setprio 1
	ds_read_b128 v[214:217], v32
	ds_read_b128 v[218:221], v32 offset:4608
	ds_read_b128 v[222:225], v32 offset:32
	ds_read_b128 v[226:229], v32 offset:4640
	ds_read_b128 v[230:233], v32 offset:64
	ds_read_b128 v[234:237], v32 offset:4672
	ds_read_b128 v[238:241], v32 offset:96
	ds_read_b128 v[244:247], v32 offset:4704
	s_waitcnt lgkmcnt(7)
	v_mfma_f32_32x32x16_bf16 v[114:129], v[214:217], v[146:149], v[98:113]
	s_waitcnt lgkmcnt(6)
	v_mfma_f32_32x32x16_bf16 v[130:145], v[218:221], v[146:149], v[98:113]
	s_waitcnt lgkmcnt(5)
	v_mfma_f32_32x32x16_bf16 v[114:129], v[222:225], v[150:153], v[114:129]
	s_waitcnt lgkmcnt(4)
	v_mfma_f32_32x32x16_bf16 v[130:145], v[226:229], v[150:153], v[130:145]
	s_waitcnt lgkmcnt(3)
	v_mfma_f32_32x32x16_bf16 v[114:129], v[230:233], v[154:157], v[114:129]
	s_waitcnt lgkmcnt(2)
	v_mfma_f32_32x32x16_bf16 v[130:145], v[234:237], v[154:157], v[130:145]
	s_waitcnt lgkmcnt(1)
	v_mfma_f32_32x32x16_bf16 v[114:129], v[238:241], v[158:161], v[114:129]
	s_waitcnt lgkmcnt(0)
	v_mfma_f32_32x32x16_bf16 v[130:145], v[244:247], v[158:161], v[130:145]
	s_setprio 0
	s_cmp_le_i32 s18, s76
	s_cbranch_scc1 .LBB0_828
	v_add_u32_e32 v32, s18, v190
	v_subrev_u32_e32 v200, 31, v32
	v_subrev_u32_e32 v198, 63, v32
	v_cmp_le_i32_e32 vcc, v200, v166
	s_nop 4
	v_cndmask_b32_e32 v130, v208, v130, vcc
	v_cmp_lt_i32_e32 vcc, v198, v166
	s_nop 1
	v_cndmask_b32_e32 v115, v208, v115, vcc
	v_cmp_le_i32_e32 vcc, v198, v166
	v_subrev_u32_e32 v198, 30, v32
	s_nop 0
	v_cndmask_b32_e32 v114, v208, v114, vcc
	v_cmp_le_i32_e32 vcc, v198, v166
	v_subrev_u32_e32 v198, 61, v32
	s_nop 0
	v_cndmask_b32_e32 v131, v208, v131, vcc
	v_cmp_le_i32_e32 vcc, v198, v166
	v_subrev_u32_e32 v198, 29, v32
	s_nop 0
	v_cndmask_b32_e32 v116, v208, v116, vcc
	v_cmp_le_i32_e32 vcc, v198, v166
	v_subrev_u32_e32 v198, 60, v32
	s_nop 0
	v_cndmask_b32_e32 v132, v208, v132, vcc
	v_cmp_le_i32_e32 vcc, v198, v166
	v_subrev_u32_e32 v198, 28, v32
	s_nop 0
	v_cndmask_b32_e32 v117, v208, v117, vcc
	v_cmp_le_i32_e32 vcc, v198, v166
	v_subrev_u32_e32 v198, 55, v32
	s_nop 0
	v_cndmask_b32_e32 v133, v208, v133, vcc
	v_cmp_le_i32_e32 vcc, v198, v166
	v_subrev_u32_e32 v198, 23, v32
	s_nop 0
	v_cndmask_b32_e32 v118, v208, v118, vcc
	v_cmp_le_i32_e32 vcc, v198, v166
	v_subrev_u32_e32 v198, 54, v32
	s_nop 0
	v_cndmask_b32_e32 v134, v208, v134, vcc
	v_cmp_le_i32_e32 vcc, v198, v166
	v_subrev_u32_e32 v198, 22, v32
	s_nop 0
	v_cndmask_b32_e32 v119, v208, v119, vcc
	v_cmp_le_i32_e32 vcc, v198, v166
	v_subrev_u32_e32 v198, 53, v32
	s_nop 0
	v_cndmask_b32_e32 v135, v208, v135, vcc
	v_cmp_le_i32_e32 vcc, v198, v166
	v_subrev_u32_e32 v198, 21, v32
	s_nop 0
	v_cndmask_b32_e32 v120, v208, v120, vcc
	v_cmp_le_i32_e32 vcc, v198, v166
	v_subrev_u32_e32 v198, 52, v32
	s_nop 0
	v_cndmask_b32_e32 v136, v208, v136, vcc
	v_cmp_le_i32_e32 vcc, v198, v166
	v_subrev_u32_e32 v198, 20, v32
	s_nop 0
	v_cndmask_b32_e32 v121, v208, v121, vcc
	v_cmp_le_i32_e32 vcc, v198, v166
	v_subrev_u32_e32 v198, 47, v32
	s_nop 0
	v_cndmask_b32_e32 v137, v208, v137, vcc
	v_cmp_le_i32_e32 vcc, v198, v166
	v_add_u32_e32 v198, -15, v32
	s_nop 0
	v_cndmask_b32_e32 v122, v208, v122, vcc
	v_cmp_le_i32_e32 vcc, v198, v166
	v_subrev_u32_e32 v198, 46, v32
	s_nop 0
	v_cndmask_b32_e32 v138, v208, v138, vcc
	v_cmp_le_i32_e32 vcc, v198, v166
	v_add_u32_e32 v198, -14, v32
	s_nop 0
	v_cndmask_b32_e32 v123, v208, v123, vcc
	v_cmp_le_i32_e32 vcc, v198, v166
	v_subrev_u32_e32 v198, 45, v32
	s_nop 0
	v_cndmask_b32_e32 v139, v208, v139, vcc
	v_cmp_le_i32_e32 vcc, v198, v166
	v_add_u32_e32 v198, -13, v32
	s_nop 0
	v_cndmask_b32_e32 v124, v208, v124, vcc
	v_cmp_le_i32_e32 vcc, v198, v166
	v_subrev_u32_e32 v198, 44, v32
	s_nop 0
	v_cndmask_b32_e32 v140, v208, v140, vcc
	v_cmp_le_i32_e32 vcc, v198, v166
	v_add_u32_e32 v198, -12, v32
	s_nop 0
	v_cndmask_b32_e32 v125, v208, v125, vcc
	v_cmp_le_i32_e32 vcc, v198, v166
	v_subrev_u32_e32 v198, 39, v32
	s_nop 0
	v_cndmask_b32_e32 v141, v208, v141, vcc
	v_cmp_le_i32_e32 vcc, v198, v166
	v_add_u32_e32 v198, -7, v32
	s_nop 0
	v_cndmask_b32_e32 v126, v208, v126, vcc
	v_cmp_le_i32_e32 vcc, v198, v166
	v_subrev_u32_e32 v198, 38, v32
	s_nop 0
	v_cndmask_b32_e32 v142, v208, v142, vcc
	v_cmp_le_i32_e32 vcc, v198, v166
	v_add_u32_e32 v198, -6, v32
	s_nop 0
	v_cndmask_b32_e32 v127, v208, v127, vcc
	v_cmp_le_i32_e32 vcc, v198, v166
	v_subrev_u32_e32 v198, 37, v32
	s_nop 0
	v_cndmask_b32_e32 v143, v208, v143, vcc
	v_cmp_le_i32_e32 vcc, v198, v166
	v_add_u32_e32 v198, -5, v32
	s_nop 0
	v_cndmask_b32_e32 v128, v208, v128, vcc
	v_cmp_le_i32_e32 vcc, v198, v166
	v_subrev_u32_e32 v198, 36, v32
	v_add_u32_e32 v32, -4, v32
	v_cndmask_b32_e32 v144, v208, v144, vcc
	v_cmp_le_i32_e32 vcc, v198, v166
	s_nop 1
	v_cndmask_b32_e32 v129, v208, v129, vcc
	v_cmp_le_i32_e32 vcc, v32, v166
	s_nop 1
	v_cndmask_b32_e32 v145, v208, v145, vcc

.LBB0_837:
	v_exp_f32_e32 v198, v114
	v_exp_f32_e32 v200, v130
	v_exp_f32_e32 v32, v115
	v_exp_f32_e32 v114, v131
	v_exp_f32_e32 v212, v132
	v_add_f32_e32 v115, v200, v198
	v_exp_f32_e32 v122, v122
	v_pk_add_f32 v[130:131], v[114:115], v[32:33]
	v_exp_f32_e32 v115, v116
	v_pk_add_f32 v[130:131], v[130:131], v[130:131] op_sel_hi:[0,1]
	v_exp_f32_e32 v130, v117
	v_exp_f32_e32 v116, v133
	v_add_f32_e32 v117, v212, v115
	s_mulk_i32 s35, 0x5000
	v_pk_add_f32 v[132:133], v[116:117], v[130:131]
	s_nop 0
	v_pk_add_f32 v[132:133], v[132:133], v[132:133] op_sel_hi:[0,1]
	v_exp_f32_e32 v117, v118
	v_exp_f32_e32 v131, v134
	v_exp_f32_e32 v132, v119
	v_exp_f32_e32 v134, v135
	v_add_f32_e32 v135, v131, v117
	v_pk_add_f32 v[118:119], v[134:135], v[132:133]
	s_nop 0
	v_pk_add_f32 v[202:203], v[118:119], v[118:119] op_sel_hi:[0,1]
	v_exp_f32_e32 v133, v120
	v_exp_f32_e32 v135, v136
	v_exp_f32_e32 v202, v121
	v_exp_f32_e32 v136, v137
	v_add_f32_e32 v137, v135, v133
	v_pk_add_f32 v[118:119], v[136:137], v[202:203]
	s_nop 0
	v_pk_add_f32 v[120:121], v[118:119], v[118:119] op_sel_hi:[0,1]
	v_exp_f32_e32 v137, v138
	v_exp_f32_e32 v120, v123
	v_exp_f32_e32 v138, v139
	v_exp_f32_e32 v203, v142
	v_add_f32_e32 v139, v137, v122
	v_exp_f32_e32 v142, v143
	v_pk_add_f32 v[118:119], v[138:139], v[120:121]
	v_exp_f32_e32 v121, v124
	v_pk_add_f32 v[204:205], v[118:119], v[118:119] op_sel_hi:[0,1]
	v_exp_f32_e32 v139, v140
	v_exp_f32_e32 v204, v125
	v_exp_f32_e32 v124, v141
	v_cvt_pk_bf16_f32 v122, v122, v120
	v_add_f32_e32 v125, v139, v121
	v_cvt_pk_bf16_f32 v123, v121, v204
	v_pk_add_f32 v[118:119], v[124:125], v[204:205]
	v_exp_f32_e32 v125, v126
	v_pk_add_f32 v[140:141], v[118:119], v[118:119] op_sel_hi:[0,1]
	v_exp_f32_e32 v140, v127
	v_cvt_pk_bf16_f32 v126, v200, v114
	v_add_f32_e32 v143, v203, v125
	v_cvt_pk_bf16_f32 v114, v137, v138
	v_pk_add_f32 v[118:119], v[142:143], v[140:141]
	v_exp_f32_e32 v141, v128
	v_pk_add_f32 v[210:211], v[118:119], v[118:119] op_sel_hi:[0,1]
	v_exp_f32_e32 v143, v144
	v_exp_f32_e32 v210, v129
	v_exp_f32_e32 v144, v145
	v_cvt_pk_bf16_f32 v127, v212, v116
	v_add_f32_e32 v145, v143, v141
	v_cvt_pk_bf16_f32 v120, v117, v132
	v_pk_add_f32 v[118:119], v[144:145], v[210:211]
	v_cvt_pk_bf16_f32 v128, v131, v134
	v_add_f32_e32 v145, v118, v119
	v_cvt_pk_bf16_f32 v118, v198, v32
	v_cvt_pk_bf16_f32 v119, v115, v130
	v_cvt_pk_bf16_f32 v115, v139, v124
	v_cvt_pk_bf16_f32 v124, v125, v140
	v_cvt_pk_bf16_f32 v116, v203, v142
	v_cvt_pk_bf16_f32 v121, v133, v202
	v_cvt_pk_bf16_f32 v125, v141, v210
	v_cvt_pk_bf16_f32 v129, v135, v136
	v_cvt_pk_bf16_f32 v117, v143, v144
	v_add_u32_e32 v32, s35, v194
	s_setprio 1
	ds_read_b64_tr_b16 v[214:215], v32 offset:18432
	ds_read_b64_tr_b16 v[216:217], v32 offset:20992
	ds_read_b64_tr_b16 v[218:219], v32 offset:18496
	ds_read_b64_tr_b16 v[220:221], v32 offset:21056
	ds_read_b64_tr_b16 v[222:223], v32 offset:18560
	ds_read_b64_tr_b16 v[224:225], v32 offset:21120
	ds_read_b64_tr_b16 v[226:227], v32 offset:18624
	ds_read_b64_tr_b16 v[228:229], v32 offset:21184
	ds_read_b64_tr_b16 v[230:231], v32 offset:23552
	ds_read_b64_tr_b16 v[232:233], v32 offset:26112
	ds_read_b64_tr_b16 v[234:235], v32 offset:23616
	ds_read_b64_tr_b16 v[236:237], v32 offset:26176
	ds_read_b64_tr_b16 v[238:239], v32 offset:23680
	ds_read_b64_tr_b16 v[240:241], v32 offset:26240
	s_waitcnt lgkmcnt(12)
	v_mfma_f32_32x32x16_bf16 v[82:97], v[118:121], v[214:217], v[82:97]
	v_add_f32_e32 v182, v182, v145
	ds_read_b64_tr_b16 v[214:215], v32 offset:23744
	ds_read_b64_tr_b16 v[216:217], v32 offset:26304
	s_waitcnt lgkmcnt(12)
	v_mfma_f32_32x32x16_bf16 v[66:81], v[118:121], v[218:221], v[66:81]
	ds_read_b64_tr_b16 v[218:219], v32 offset:28672
	ds_read_b64_tr_b16 v[220:221], v32 offset:31232
	s_waitcnt lgkmcnt(12)
	v_mfma_f32_32x32x16_bf16 v[50:65], v[118:121], v[222:225], v[50:65]
	ds_read_b64_tr_b16 v[222:223], v32 offset:28736
	ds_read_b64_tr_b16 v[224:225], v32 offset:31296
	s_waitcnt lgkmcnt(12)
	v_mfma_f32_32x32x16_bf16 v[34:49], v[118:121], v[226:229], v[34:49]
	ds_read_b64_tr_b16 v[226:227], v32 offset:28800
	ds_read_b64_tr_b16 v[228:229], v32 offset:31360
	s_waitcnt lgkmcnt(12)
	v_mfma_f32_32x32x16_bf16 v[82:97], v[122:125], v[230:233], v[82:97]
	ds_read_b64_tr_b16 v[230:231], v32 offset:28864
	ds_read_b64_tr_b16 v[232:233], v32 offset:31424
	s_waitcnt lgkmcnt(12)
	v_mfma_f32_32x32x16_bf16 v[66:81], v[122:125], v[234:237], v[66:81]
	ds_read_b64_tr_b16 v[234:235], v32 offset:33792
	ds_read_b64_tr_b16 v[236:237], v32 offset:36352
	s_waitcnt lgkmcnt(12)
	v_mfma_f32_32x32x16_bf16 v[50:65], v[122:125], v[238:241], v[50:65]
	ds_read_b64_tr_b16 v[238:239], v32 offset:33856
	ds_read_b64_tr_b16 v[240:241], v32 offset:36416
	s_waitcnt lgkmcnt(12)
	v_mfma_f32_32x32x16_bf16 v[34:49], v[122:125], v[214:217], v[34:49]
	ds_read_b64_tr_b16 v[214:215], v32 offset:33920
	ds_read_b64_tr_b16 v[216:217], v32 offset:36480
	s_waitcnt lgkmcnt(12)
	v_mfma_f32_32x32x16_bf16 v[82:97], v[126:129], v[218:221], v[82:97]
	ds_read_b64_tr_b16 v[218:219], v32 offset:33984
	ds_read_b64_tr_b16 v[220:221], v32 offset:36544
	s_waitcnt lgkmcnt(12)
	v_mfma_f32_32x32x16_bf16 v[66:81], v[126:129], v[222:225], v[66:81]
	s_waitcnt lgkmcnt(10)
	v_mfma_f32_32x32x16_bf16 v[50:65], v[126:129], v[226:229], v[50:65]
	s_waitcnt lgkmcnt(8)
	v_mfma_f32_32x32x16_bf16 v[34:49], v[126:129], v[230:233], v[34:49]
	s_waitcnt lgkmcnt(6)
	v_mfma_f32_32x32x16_bf16 v[82:97], v[114:117], v[234:237], v[82:97]
	s_waitcnt lgkmcnt(4)
	v_mfma_f32_32x32x16_bf16 v[66:81], v[114:117], v[238:241], v[66:81]
	s_waitcnt lgkmcnt(2)
	v_mfma_f32_32x32x16_bf16 v[50:65], v[114:117], v[214:217], v[50:65]
	s_waitcnt lgkmcnt(0)
	v_mfma_f32_32x32x16_bf16 v[34:49], v[114:117], v[218:221], v[34:49]
	s_setprio 0

; template <int DQK>
; __device__ __forceinline__ void attn_pass4(LAS unsigned char* lds, const bf16* Qp, int qpitch, const bf16* Kp, int kpitch, const bf16* Vp, int vpitch, int q0, f32x16 (&o)[4], float (&rl)[16]) {
;     ...
;             if (t > 0 && ATT_VIS(t - 1)) ATT_B(vprev);
.LBB0_851:
	s_cmp_lg_u32 s18, 0
	s_cselect_b64 s[72:73], -1, 0
	s_cmp_eq_u32 s18, 0
	s_mov_b32 s10, 0
	s_cbranch_scc1 .LBB0_855
	s_sub_i32 s10, s2, 64
	s_cmp_gt_i32 s10, s3
	s_cbranch_scc1 .LBB0_854
	s_mulk_i32 s24, 0x5000
	v_add_u32_e32 v32, s24, v177
	s_setprio 1
	ds_read_b64_tr_b16 v[214:215], v32 offset:18432
	ds_read_b64_tr_b16 v[216:217], v32 offset:20992
	ds_read_b64_tr_b16 v[218:219], v32 offset:18496
	ds_read_b64_tr_b16 v[220:221], v32 offset:21056
	ds_read_b64_tr_b16 v[222:223], v32 offset:18560
	ds_read_b64_tr_b16 v[224:225], v32 offset:21120
	ds_read_b64_tr_b16 v[226:227], v32 offset:18624
	ds_read_b64_tr_b16 v[228:229], v32 offset:21184
	ds_read_b64_tr_b16 v[230:231], v32 offset:23552
	ds_read_b64_tr_b16 v[232:233], v32 offset:26112
	ds_read_b64_tr_b16 v[234:235], v32 offset:23616
	ds_read_b64_tr_b16 v[236:237], v32 offset:26176
	ds_read_b64_tr_b16 v[238:239], v32 offset:23680
	ds_read_b64_tr_b16 v[240:241], v32 offset:26240
	s_waitcnt lgkmcnt(12)
	v_mfma_f32_32x32x16_bf16 v[82:97], v[126:129], v[214:217], v[82:97]
	ds_read_b64_tr_b16 v[214:215], v32 offset:23744
	ds_read_b64_tr_b16 v[216:217], v32 offset:26304
	s_waitcnt lgkmcnt(12)
	v_mfma_f32_32x32x16_bf16 v[66:81], v[126:129], v[218:221], v[66:81]
	ds_read_b64_tr_b16 v[218:219], v32 offset:28672
	ds_read_b64_tr_b16 v[220:221], v32 offset:31232
	s_waitcnt lgkmcnt(12)
	v_mfma_f32_32x32x16_bf16 v[50:65], v[126:129], v[222:225], v[50:65]
	ds_read_b64_tr_b16 v[222:223], v32 offset:28736
	ds_read_b64_tr_b16 v[224:225], v32 offset:31296
	s_waitcnt lgkmcnt(12)
	v_mfma_f32_32x32x16_bf16 v[34:49], v[126:129], v[226:229], v[34:49]
	ds_read_b64_tr_b16 v[226:227], v32 offset:28800
	ds_read_b64_tr_b16 v[228:229], v32 offset:31360
	s_waitcnt lgkmcnt(12)
	v_mfma_f32_32x32x16_bf16 v[82:97], v[122:125], v[230:233], v[82:97]
	ds_read_b64_tr_b16 v[230:231], v32 offset:28864
	ds_read_b64_tr_b16 v[232:233], v32 offset:31424
	s_waitcnt lgkmcnt(12)
	v_mfma_f32_32x32x16_bf16 v[66:81], v[122:125], v[234:237], v[66:81]
	ds_read_b64_tr_b16 v[234:235], v32 offset:33792
	ds_read_b64_tr_b16 v[236:237], v32 offset:36352
	s_waitcnt lgkmcnt(12)
	v_mfma_f32_32x32x16_bf16 v[50:65], v[122:125], v[238:241], v[50:65]
	ds_read_b64_tr_b16 v[238:239], v32 offset:33856
	ds_read_b64_tr_b16 v[240:241], v32 offset:36416
	s_waitcnt lgkmcnt(12)
	v_mfma_f32_32x32x16_bf16 v[34:49], v[122:125], v[214:217], v[34:49]
	ds_read_b64_tr_b16 v[214:215], v32 offset:33920
	ds_read_b64_tr_b16 v[216:217], v32 offset:36480
	s_waitcnt lgkmcnt(12)
	v_mfma_f32_32x32x16_bf16 v[82:97], v[118:121], v[218:221], v[82:97]
	ds_read_b64_tr_b16 v[218:219], v32 offset:33984
	ds_read_b64_tr_b16 v[220:221], v32 offset:36544
	s_waitcnt lgkmcnt(12)
	v_mfma_f32_32x32x16_bf16 v[66:81], v[118:121], v[222:225], v[66:81]
	s_waitcnt lgkmcnt(10)
	v_mfma_f32_32x32x16_bf16 v[50:65], v[118:121], v[226:229], v[50:65]
	s_waitcnt lgkmcnt(8)
	v_mfma_f32_32x32x16_bf16 v[34:49], v[118:121], v[230:233], v[34:49]
	s_waitcnt lgkmcnt(6)
	v_mfma_f32_32x32x16_bf16 v[82:97], v[114:117], v[234:237], v[82:97]
	s_waitcnt lgkmcnt(4)
	v_mfma_f32_32x32x16_bf16 v[66:81], v[114:117], v[238:241], v[66:81]
	s_waitcnt lgkmcnt(2)
	v_mfma_f32_32x32x16_bf16 v[50:65], v[114:117], v[214:217], v[50:65]
	s_waitcnt lgkmcnt(0)
	v_mfma_f32_32x32x16_bf16 v[34:49], v[114:117], v[218:221], v[34:49]
	s_setprio 0

; template <int DQK>
; __device__ __forceinline__ void attn_pass4(LAS unsigned char* lds, const bf16* Qp, int qpitch, const bf16* Kp, int kpitch, const bf16* Vp, int vpitch, int q0, f32x16 (&o)[4], float (&rl)[16]) {
;     ...
;             if (ATT_VIS(t)) ATT_A(t);
.LBB0_855:
	s_cmp_gt_i32 s10, s3
	s_cbranch_scc1 .LBB0_869
	s_bitcmp1_b32 s18, 0
	s_cselect_b32 s11, 0x2400, 0
	v_add_u32_e32 v32, s11, v188
	s_setprio 1
	ds_read_b128 v[214:217], v32
	ds_read_b128 v[218:221], v32 offset:4608
	ds_read_b128 v[222:225], v32 offset:32
	ds_read_b128 v[226:229], v32 offset:4640
	ds_read_b128 v[230:233], v32 offset:64
	ds_read_b128 v[234:237], v32 offset:4672
	ds_read_b128 v[238:241], v32 offset:96
	ds_read_b128 v[244:247], v32 offset:4704
	s_waitcnt lgkmcnt(7)
	v_mfma_f32_32x32x16_bf16 v[114:129], v[214:217], v[146:149], v[98:113]
	s_waitcnt lgkmcnt(6)
	v_mfma_f32_32x32x16_bf16 v[130:145], v[218:221], v[146:149], v[98:113]
	s_waitcnt lgkmcnt(5)
	v_mfma_f32_32x32x16_bf16 v[114:129], v[222:225], v[150:153], v[114:129]
	s_waitcnt lgkmcnt(4)
	v_mfma_f32_32x32x16_bf16 v[130:145], v[226:229], v[150:153], v[130:145]
	s_waitcnt lgkmcnt(3)
	v_mfma_f32_32x32x16_bf16 v[114:129], v[230:233], v[154:157], v[114:129]
	s_waitcnt lgkmcnt(2)
	v_mfma_f32_32x32x16_bf16 v[130:145], v[234:237], v[154:157], v[130:145]
	s_waitcnt lgkmcnt(1)
	v_mfma_f32_32x32x16_bf16 v[114:129], v[238:241], v[158:161], v[114:129]
	s_waitcnt lgkmcnt(0)
	v_mfma_f32_32x32x16_bf16 v[130:145], v[244:247], v[158:161], v[130:145]
	s_setprio 0
	s_or_b32 s11, s10, 63
	s_cmp_le_i32 s11, s76
	s_cbranch_scc1 .LBB0_858
	v_or_b32_e32 v32, s10, v190
	v_or_b32_e32 v179, 32, v32
	v_cmp_le_i32_e32 vcc, v179, v166
	v_or_b32_e32 v179, 33, v32
	s_nop 3
	v_cndmask_b32_e32 v130, v208, v130, vcc
	v_cmp_lt_i32_e32 vcc, v32, v166
	s_nop 1
	v_cndmask_b32_e32 v115, v208, v115, vcc
	v_cmp_le_i32_e32 vcc, v32, v166
	s_nop 1
	v_cndmask_b32_e32 v114, v208, v114, vcc
	v_cmp_le_i32_e32 vcc, v179, v166
	v_or_b32_e32 v179, 2, v32
	s_nop 0
	v_cndmask_b32_e32 v131, v208, v131, vcc
	v_cmp_le_i32_e32 vcc, v179, v166
	v_or_b32_e32 v179, 34, v32
	s_nop 0
	v_cndmask_b32_e32 v116, v208, v116, vcc
	v_cmp_le_i32_e32 vcc, v179, v166
	v_or_b32_e32 v179, 3, v32
	s_nop 0
	v_cndmask_b32_e32 v132, v208, v132, vcc
	v_cmp_le_i32_e32 vcc, v179, v166
	v_or_b32_e32 v179, 35, v32
	s_nop 0
	v_cndmask_b32_e32 v117, v208, v117, vcc
	v_cmp_le_i32_e32 vcc, v179, v166
	v_or_b32_e32 v179, 8, v32
	s_nop 0
	v_cndmask_b32_e32 v133, v208, v133, vcc
	v_cmp_le_i32_e32 vcc, v179, v166
	v_or_b32_e32 v179, 40, v32
	s_nop 0
	v_cndmask_b32_e32 v118, v208, v118, vcc
	v_cmp_le_i32_e32 vcc, v179, v166
	v_or_b32_e32 v179, 9, v32
	s_nop 0
	v_cndmask_b32_e32 v134, v208, v134, vcc
	v_cmp_le_i32_e32 vcc, v179, v166
	v_or_b32_e32 v179, 41, v32
	s_nop 0
	v_cndmask_b32_e32 v119, v208, v119, vcc
	v_cmp_le_i32_e32 vcc, v179, v166
	v_or_b32_e32 v179, 10, v32
	s_nop 0
	v_cndmask_b32_e32 v135, v208, v135, vcc
	v_cmp_le_i32_e32 vcc, v179, v166
	v_or_b32_e32 v179, 42, v32
	s_nop 0
	v_cndmask_b32_e32 v120, v208, v120, vcc
	v_cmp_le_i32_e32 vcc, v179, v166
	v_or_b32_e32 v179, 11, v32
	s_nop 0
	v_cndmask_b32_e32 v136, v208, v136, vcc
	v_cmp_le_i32_e32 vcc, v179, v166
	v_or_b32_e32 v179, 43, v32
	s_nop 0
	v_cndmask_b32_e32 v121, v208, v121, vcc
	v_cmp_le_i32_e32 vcc, v179, v166
	v_or_b32_e32 v179, 16, v32
	s_nop 0
	v_cndmask_b32_e32 v137, v208, v137, vcc
	v_cmp_le_i32_e32 vcc, v179, v166
	v_or_b32_e32 v179, 48, v32
	s_nop 0
	v_cndmask_b32_e32 v122, v208, v122, vcc
	v_cmp_le_i32_e32 vcc, v179, v166
	v_or_b32_e32 v179, 17, v32
	s_nop 0
	v_cndmask_b32_e32 v138, v208, v138, vcc
	v_cmp_le_i32_e32 vcc, v179, v166
	v_or_b32_e32 v179, 49, v32
	s_nop 0
	v_cndmask_b32_e32 v123, v208, v123, vcc
	v_cmp_le_i32_e32 vcc, v179, v166
	v_or_b32_e32 v179, 18, v32
	s_nop 0
	v_cndmask_b32_e32 v139, v208, v139, vcc
	v_cmp_le_i32_e32 vcc, v179, v166
	v_or_b32_e32 v179, 50, v32
	s_nop 0
	v_cndmask_b32_e32 v124, v208, v124, vcc
	v_cmp_le_i32_e32 vcc, v179, v166
	v_or_b32_e32 v179, 19, v32
	s_nop 0
	v_cndmask_b32_e32 v140, v208, v140, vcc
	v_cmp_le_i32_e32 vcc, v179, v166
	v_or_b32_e32 v179, 51, v32
	s_nop 0
	v_cndmask_b32_e32 v125, v208, v125, vcc
	v_cmp_le_i32_e32 vcc, v179, v166
	v_or_b32_e32 v179, 24, v32
	s_nop 0
	v_cndmask_b32_e32 v141, v208, v141, vcc
	v_cmp_le_i32_e32 vcc, v179, v166
	v_or_b32_e32 v179, 56, v32
	s_nop 0
	v_cndmask_b32_e32 v126, v208, v126, vcc
	v_cmp_le_i32_e32 vcc, v179, v166
	v_or_b32_e32 v179, 25, v32
	s_nop 0
	v_cndmask_b32_e32 v142, v208, v142, vcc
	v_cmp_le_i32_e32 vcc, v179, v166
	v_or_b32_e32 v179, 57, v32
	s_nop 0
	v_cndmask_b32_e32 v127, v208, v127, vcc
	v_cmp_le_i32_e32 vcc, v179, v166
	v_or_b32_e32 v179, 26, v32
	s_nop 0
	v_cndmask_b32_e32 v143, v208, v143, vcc
	v_cmp_le_i32_e32 vcc, v179, v166
	v_or_b32_e32 v179, 58, v32
	s_nop 0
	v_cndmask_b32_e32 v128, v208, v128, vcc
	v_cmp_le_i32_e32 vcc, v179, v166
	v_or_b32_e32 v179, 27, v32
	v_or_b32_e32 v32, 59, v32
	v_cndmask_b32_e32 v144, v208, v144, vcc
	v_cmp_le_i32_e32 vcc, v179, v166
	s_nop 1
	v_cndmask_b32_e32 v129, v208, v129, vcc
	v_cmp_le_i32_e32 vcc, v32, v166
	s_nop 1
	v_cndmask_b32_e32 v145, v208, v145, vcc

; template <int DQK>
; __device__ __forceinline__ void attn_pass4(LAS unsigned char* lds, const bf16* Qp, int qpitch, const bf16* Kp, int kpitch, const bf16* Vp, int vpitch, int q0, f32x16 (&o)[4], float (&rl)[16]) {
;     ...
;         if (ATT_VIS(NT - 1)) ATT_B(vprev);
.LBB0_871:
	s_cmp_gt_i32 s80, 5
	s_cbranch_scc0 .LBB0_873
	s_mul_i32 s2, s26, 0x5000
	s_add_i32 s2, s2, 0
	v_add_u32_e32 v32, s2, v176
	v_add3_u32 v32, v32, v184, v186
	s_setprio 1
	ds_read_b64_tr_b16 v[214:215], v32 offset:18432
	ds_read_b64_tr_b16 v[216:217], v32 offset:20992
	ds_read_b64_tr_b16 v[218:219], v32 offset:18496
	ds_read_b64_tr_b16 v[220:221], v32 offset:21056
	ds_read_b64_tr_b16 v[222:223], v32 offset:18560
	ds_read_b64_tr_b16 v[224:225], v32 offset:21120
	ds_read_b64_tr_b16 v[226:227], v32 offset:18624
	ds_read_b64_tr_b16 v[228:229], v32 offset:21184
	ds_read_b64_tr_b16 v[230:231], v32 offset:23552
	ds_read_b64_tr_b16 v[232:233], v32 offset:26112
	ds_read_b64_tr_b16 v[234:235], v32 offset:23616
	ds_read_b64_tr_b16 v[236:237], v32 offset:26176
	ds_read_b64_tr_b16 v[238:239], v32 offset:23680
	ds_read_b64_tr_b16 v[240:241], v32 offset:26240
	s_waitcnt lgkmcnt(12)
	v_mfma_f32_32x32x16_bf16 v[82:97], v[126:129], v[214:217], v[82:97]
	ds_read_b64_tr_b16 v[214:215], v32 offset:23744
	ds_read_b64_tr_b16 v[216:217], v32 offset:26304
	s_waitcnt lgkmcnt(12)
	v_mfma_f32_32x32x16_bf16 v[66:81], v[126:129], v[218:221], v[66:81]
	ds_read_b64_tr_b16 v[218:219], v32 offset:28672
	ds_read_b64_tr_b16 v[220:221], v32 offset:31232
	s_waitcnt lgkmcnt(12)
	v_mfma_f32_32x32x16_bf16 v[50:65], v[126:129], v[222:225], v[50:65]
	ds_read_b64_tr_b16 v[222:223], v32 offset:28736
	ds_read_b64_tr_b16 v[224:225], v32 offset:31296
	s_waitcnt lgkmcnt(12)
	v_mfma_f32_32x32x16_bf16 v[34:49], v[126:129], v[226:229], v[34:49]
	ds_read_b64_tr_b16 v[226:227], v32 offset:28800
	ds_read_b64_tr_b16 v[228:229], v32 offset:31360
	s_waitcnt lgkmcnt(12)
	v_mfma_f32_32x32x16_bf16 v[82:97], v[122:125], v[230:233], v[82:97]
	ds_read_b64_tr_b16 v[230:231], v32 offset:28864
	ds_read_b64_tr_b16 v[232:233], v32 offset:31424
	s_waitcnt lgkmcnt(12)
	v_mfma_f32_32x32x16_bf16 v[66:81], v[122:125], v[234:237], v[66:81]
	ds_read_b64_tr_b16 v[234:235], v32 offset:33792
	ds_read_b64_tr_b16 v[236:237], v32 offset:36352
	s_waitcnt lgkmcnt(12)
	v_mfma_f32_32x32x16_bf16 v[50:65], v[122:125], v[238:241], v[50:65]
	ds_read_b64_tr_b16 v[238:239], v32 offset:33856
	ds_read_b64_tr_b16 v[240:241], v32 offset:36416
	s_waitcnt lgkmcnt(12)
	v_mfma_f32_32x32x16_bf16 v[34:49], v[122:125], v[214:217], v[34:49]
	ds_read_b64_tr_b16 v[214:215], v32 offset:33920
	ds_read_b64_tr_b16 v[216:217], v32 offset:36480
	s_waitcnt lgkmcnt(12)
	v_mfma_f32_32x32x16_bf16 v[82:97], v[118:121], v[218:221], v[82:97]
	ds_read_b64_tr_b16 v[218:219], v32 offset:33984
	ds_read_b64_tr_b16 v[220:221], v32 offset:36544
	s_waitcnt lgkmcnt(12)
	v_mfma_f32_32x32x16_bf16 v[66:81], v[118:121], v[222:225], v[66:81]
	s_waitcnt lgkmcnt(10)
	v_mfma_f32_32x32x16_bf16 v[50:65], v[118:121], v[226:229], v[50:65]
	s_waitcnt lgkmcnt(8)
	v_mfma_f32_32x32x16_bf16 v[34:49], v[118:121], v[230:233], v[34:49]
	s_waitcnt lgkmcnt(6)
	v_mfma_f32_32x32x16_bf16 v[82:97], v[114:117], v[234:237], v[82:97]
	s_waitcnt lgkmcnt(4)
	v_mfma_f32_32x32x16_bf16 v[66:81], v[114:117], v[238:241], v[66:81]
	s_waitcnt lgkmcnt(2)
	v_mfma_f32_32x32x16_bf16 v[50:65], v[114:117], v[214:217], v[50:65]
	s_waitcnt lgkmcnt(0)
	v_mfma_f32_32x32x16_bf16 v[34:49], v[114:117], v[218:221], v[34:49]
	s_setprio 0

.LBB0_2155:
	s_sub_i32 s61, s75, 63
	s_cmp_gt_i32 s61, s25
	s_cbranch_scc1 .LBB0_2168
	s_bitcmp1_b32 s60, 0
	s_cselect_b32 s60, 0x6400, 0
	v_add_u32_e32 v0, s60, v200
	s_setprio 1
	ds_read_b128 v[214:217], v0
	ds_read_b128 v[218:221], v0 offset:32
	ds_read_b128 v[222:225], v0 offset:12800
	ds_read_b128 v[226:229], v0 offset:12832
	ds_read_b128 v[230:233], v0 offset:64
	ds_read_b128 v[234:237], v0 offset:12864
	ds_read_b128 v[238:241], v0 offset:96
	ds_read_b128 v[244:247], v0 offset:12896
	ds_read_b128 v[248:251], v0 offset:128
	s_waitcnt lgkmcnt(8)
	v_mfma_f32_32x32x16_bf16 v[96:111], v[214:217], v[128:131], v[80:95]
	ds_read_b128 v[214:217], v0 offset:12928
	s_waitcnt lgkmcnt(8)
	v_mfma_f32_32x32x16_bf16 v[96:111], v[218:221], v[132:135], v[96:111]
	ds_read_b128 v[218:221], v0 offset:160
	s_waitcnt lgkmcnt(8)
	v_mfma_f32_32x32x16_bf16 v[112:127], v[222:225], v[128:131], v[80:95]
	ds_read_b128 v[222:225], v0 offset:12960
	s_waitcnt lgkmcnt(8)
	v_mfma_f32_32x32x16_bf16 v[112:127], v[226:229], v[132:135], v[112:127]
	ds_read_b128 v[226:229], v0 offset:192
	s_waitcnt lgkmcnt(8)
	v_mfma_f32_32x32x16_bf16 v[96:111], v[230:233], v[136:139], v[96:111]
	ds_read_b128 v[230:233], v0 offset:12992
	s_waitcnt lgkmcnt(8)
	v_mfma_f32_32x32x16_bf16 v[112:127], v[234:237], v[136:139], v[112:127]
	ds_read_b128 v[234:237], v0 offset:224
	s_waitcnt lgkmcnt(8)
	v_mfma_f32_32x32x16_bf16 v[96:111], v[238:241], v[140:143], v[96:111]
	ds_read_b128 v[238:241], v0 offset:13024
	s_waitcnt lgkmcnt(8)
	v_mfma_f32_32x32x16_bf16 v[112:127], v[244:247], v[140:143], v[112:127]
	ds_read_b128 v[244:247], v0 offset:256
	s_waitcnt lgkmcnt(8)
	v_mfma_f32_32x32x16_bf16 v[96:111], v[248:251], v[144:147], v[96:111]
	ds_read_b128 v[248:251], v0 offset:13056
	s_waitcnt lgkmcnt(8)
	v_mfma_f32_32x32x16_bf16 v[112:127], v[214:217], v[144:147], v[112:127]
	ds_read_b128 v[214:217], v0 offset:288
	s_waitcnt lgkmcnt(8)
	v_mfma_f32_32x32x16_bf16 v[96:111], v[218:221], v[148:151], v[96:111]
	ds_read_b128 v[218:221], v0 offset:13088
	s_waitcnt lgkmcnt(8)
	v_mfma_f32_32x32x16_bf16 v[112:127], v[222:225], v[148:151], v[112:127]
	ds_read_b128 v[222:225], v0 offset:320
	s_waitcnt lgkmcnt(8)
	v_mfma_f32_32x32x16_bf16 v[96:111], v[226:229], v[152:155], v[96:111]
	ds_read_b128 v[226:229], v0 offset:13120
	s_waitcnt lgkmcnt(8)
	v_mfma_f32_32x32x16_bf16 v[112:127], v[230:233], v[152:155], v[112:127]
	ds_read_b128 v[230:233], v0 offset:352
	s_waitcnt lgkmcnt(8)
	v_mfma_f32_32x32x16_bf16 v[96:111], v[234:237], v[156:159], v[96:111]
	ds_read_b128 v[234:237], v0 offset:13152
	s_waitcnt lgkmcnt(8)
	v_mfma_f32_32x32x16_bf16 v[112:127], v[238:241], v[156:159], v[112:127]
	s_waitcnt lgkmcnt(7)
	v_mfma_f32_32x32x16_bf16 v[96:111], v[244:247], v[160:163], v[96:111]
	s_waitcnt lgkmcnt(6)
	v_mfma_f32_32x32x16_bf16 v[112:127], v[248:251], v[160:163], v[112:127]
	s_waitcnt lgkmcnt(5)
	v_mfma_f32_32x32x16_bf16 v[96:111], v[214:217], v[164:167], v[96:111]
	s_waitcnt lgkmcnt(4)
	v_mfma_f32_32x32x16_bf16 v[112:127], v[218:221], v[164:167], v[112:127]
	s_waitcnt lgkmcnt(3)
	v_mfma_f32_32x32x16_bf16 v[96:111], v[222:225], v[168:171], v[96:111]
	s_waitcnt lgkmcnt(2)
	v_mfma_f32_32x32x16_bf16 v[112:127], v[226:229], v[168:171], v[112:127]
	s_waitcnt lgkmcnt(1)
	v_mfma_f32_32x32x16_bf16 v[96:111], v[230:233], v[172:175], v[96:111]
	s_waitcnt lgkmcnt(0)
	v_mfma_f32_32x32x16_bf16 v[112:127], v[234:237], v[172:175], v[112:127]
	s_setprio 0
	s_cmp_le_i32 s75, s68
	s_cbranch_scc1 .LBB0_2158
	v_add_u32_e32 v0, s75, v201
	v_subrev_u32_e32 v4, 31, v0
	v_subrev_u32_e32 v3, 63, v0
	v_cmp_le_i32_e32 vcc, v4, v197
	s_nop 4
	v_cndmask_b32_e32 v112, v194, v112, vcc
	v_cmp_lt_i32_e32 vcc, v3, v197
	s_nop 1
	v_cndmask_b32_e32 v97, v194, v97, vcc
	v_cmp_le_i32_e32 vcc, v3, v197
	v_subrev_u32_e32 v3, 30, v0
	s_nop 0
	v_cndmask_b32_e32 v96, v194, v96, vcc
	v_cmp_le_i32_e32 vcc, v3, v197
	v_subrev_u32_e32 v3, 61, v0
	s_nop 0
	v_cndmask_b32_e32 v113, v194, v113, vcc
	v_cmp_le_i32_e32 vcc, v3, v197
	v_subrev_u32_e32 v3, 29, v0
	s_nop 0
	v_cndmask_b32_e32 v98, v194, v98, vcc
	v_cmp_le_i32_e32 vcc, v3, v197
	v_subrev_u32_e32 v3, 60, v0
	s_nop 0
	v_cndmask_b32_e32 v114, v194, v114, vcc
	v_cmp_le_i32_e32 vcc, v3, v197
	v_subrev_u32_e32 v3, 28, v0
	s_nop 0
	v_cndmask_b32_e32 v99, v194, v99, vcc
	v_cmp_le_i32_e32 vcc, v3, v197
	v_subrev_u32_e32 v3, 55, v0
	s_nop 0
	v_cndmask_b32_e32 v115, v194, v115, vcc
	v_cmp_le_i32_e32 vcc, v3, v197
	v_subrev_u32_e32 v3, 23, v0
	s_nop 0
	v_cndmask_b32_e32 v100, v194, v100, vcc
	v_cmp_le_i32_e32 vcc, v3, v197
	v_subrev_u32_e32 v3, 54, v0
	s_nop 0
	v_cndmask_b32_e32 v116, v194, v116, vcc
	v_cmp_le_i32_e32 vcc, v3, v197
	v_subrev_u32_e32 v3, 22, v0
	s_nop 0
	v_cndmask_b32_e32 v101, v194, v101, vcc
	v_cmp_le_i32_e32 vcc, v3, v197
	v_subrev_u32_e32 v3, 53, v0
	s_nop 0
	v_cndmask_b32_e32 v117, v194, v117, vcc
	v_cmp_le_i32_e32 vcc, v3, v197
	v_subrev_u32_e32 v3, 21, v0
	s_nop 0
	v_cndmask_b32_e32 v102, v194, v102, vcc
	v_cmp_le_i32_e32 vcc, v3, v197
	v_subrev_u32_e32 v3, 52, v0
	s_nop 0
	v_cndmask_b32_e32 v118, v194, v118, vcc
	v_cmp_le_i32_e32 vcc, v3, v197
	v_subrev_u32_e32 v3, 20, v0
	s_nop 0
	v_cndmask_b32_e32 v103, v194, v103, vcc
	v_cmp_le_i32_e32 vcc, v3, v197
	v_subrev_u32_e32 v3, 47, v0
	s_nop 0
	v_cndmask_b32_e32 v119, v194, v119, vcc
	v_cmp_le_i32_e32 vcc, v3, v197
	v_add_u32_e32 v3, -15, v0
	s_nop 0
	v_cndmask_b32_e32 v104, v194, v104, vcc
	v_cmp_le_i32_e32 vcc, v3, v197
	v_subrev_u32_e32 v3, 46, v0
	s_nop 0
	v_cndmask_b32_e32 v120, v194, v120, vcc
	v_cmp_le_i32_e32 vcc, v3, v197
	v_add_u32_e32 v3, -14, v0
	s_nop 0
	v_cndmask_b32_e32 v105, v194, v105, vcc
	v_cmp_le_i32_e32 vcc, v3, v197
	v_subrev_u32_e32 v3, 45, v0
	s_nop 0
	v_cndmask_b32_e32 v121, v194, v121, vcc
	v_cmp_le_i32_e32 vcc, v3, v197
	v_add_u32_e32 v3, -13, v0
	s_nop 0
	v_cndmask_b32_e32 v106, v194, v106, vcc
	v_cmp_le_i32_e32 vcc, v3, v197
	v_subrev_u32_e32 v3, 44, v0
	s_nop 0
	v_cndmask_b32_e32 v122, v194, v122, vcc
	v_cmp_le_i32_e32 vcc, v3, v197
	v_add_u32_e32 v3, -12, v0
	s_nop 0
	v_cndmask_b32_e32 v107, v194, v107, vcc
	v_cmp_le_i32_e32 vcc, v3, v197
	v_subrev_u32_e32 v3, 39, v0
	s_nop 0
	v_cndmask_b32_e32 v123, v194, v123, vcc
	v_cmp_le_i32_e32 vcc, v3, v197
	v_add_u32_e32 v3, -7, v0
	s_nop 0
	v_cndmask_b32_e32 v108, v194, v108, vcc
	v_cmp_le_i32_e32 vcc, v3, v197
	v_subrev_u32_e32 v3, 38, v0
	s_nop 0
	v_cndmask_b32_e32 v124, v194, v124, vcc
	v_cmp_le_i32_e32 vcc, v3, v197
	v_add_u32_e32 v3, -6, v0
	s_nop 0
	v_cndmask_b32_e32 v109, v194, v109, vcc
	v_cmp_le_i32_e32 vcc, v3, v197
	v_subrev_u32_e32 v3, 37, v0
	s_nop 0
	v_cndmask_b32_e32 v125, v194, v125, vcc
	v_cmp_le_i32_e32 vcc, v3, v197
	v_add_u32_e32 v3, -5, v0
	s_nop 0
	v_cndmask_b32_e32 v110, v194, v110, vcc
	v_cmp_le_i32_e32 vcc, v3, v197
	v_subrev_u32_e32 v3, 36, v0
	v_add_u32_e32 v0, -4, v0
	v_cndmask_b32_e32 v126, v194, v126, vcc
	v_cmp_le_i32_e32 vcc, v3, v197
	s_nop 1
	v_cndmask_b32_e32 v111, v194, v111, vcc
	v_cmp_le_i32_e32 vcc, v0, v197
	s_nop 1
	v_cndmask_b32_e32 v127, v194, v127, vcc

.LBB0_2167:
	v_exp_f32_e32 v3, v96
	v_exp_f32_e32 v12, v112
	v_exp_f32_e32 v0, v97
	v_exp_f32_e32 v6, v113
	v_exp_f32_e32 v13, v114
	v_add_f32_e32 v7, v12, v3
	v_exp_f32_e32 v14, v115
	v_pk_add_f32 v[4:5], v[6:7], v[0:1]
	v_exp_f32_e32 v7, v98
	v_pk_add_f32 v[10:11], v[4:5], v[4:5] op_sel_hi:[0,1]
	v_exp_f32_e32 v10, v99
	v_exp_f32_e32 v96, v121
	v_add_f32_e32 v15, v13, v7
	s_mulk_i32 s78, 0x5000
	v_pk_add_f32 v[4:5], v[14:15], v[10:11]
	v_exp_f32_e32 v11, v100
	v_pk_add_f32 v[98:99], v[4:5], v[4:5] op_sel_hi:[0,1]
	v_exp_f32_e32 v15, v116
	v_exp_f32_e32 v98, v101
	v_exp_f32_e32 v100, v117
	v_cvt_pk_bf16_f32 v12, v12, v6
	v_add_f32_e32 v101, v15, v11
	v_cvt_pk_bf16_f32 v13, v13, v14
	v_pk_add_f32 v[4:5], v[100:101], v[98:99]
	v_exp_f32_e32 v99, v102
	v_pk_add_f32 v[112:113], v[4:5], v[4:5] op_sel_hi:[0,1]
	v_exp_f32_e32 v101, v118
	v_exp_f32_e32 v112, v103
	v_exp_f32_e32 v102, v119
	v_cvt_pk_bf16_f32 v6, v11, v98
	v_add_f32_e32 v103, v101, v99
	v_cvt_pk_bf16_f32 v14, v15, v100
	v_pk_add_f32 v[4:5], v[102:103], v[112:113]
	v_exp_f32_e32 v103, v104
	v_pk_add_f32 v[8:9], v[4:5], v[4:5] op_sel_hi:[0,1]
	v_exp_f32_e32 v113, v120
	v_exp_f32_e32 v8, v105
	v_cvt_pk_bf16_f32 v15, v101, v102
	v_add_f32_e32 v97, v113, v103
	v_pk_add_f32 v[4:5], v[96:97], v[8:9]
	v_exp_f32_e32 v9, v106
	v_pk_add_f32 v[104:105], v[4:5], v[4:5] op_sel_hi:[0,1]
	v_exp_f32_e32 v97, v122
	v_exp_f32_e32 v104, v107
	v_exp_f32_e32 v106, v123
	v_cvt_pk_bf16_f32 v8, v103, v8
	v_add_f32_e32 v107, v97, v9
	v_cvt_pk_bf16_f32 v96, v113, v96
	v_pk_add_f32 v[4:5], v[106:107], v[104:105]
	v_exp_f32_e32 v105, v108
	v_pk_add_f32 v[114:115], v[4:5], v[4:5] op_sel_hi:[0,1]
	v_exp_f32_e32 v107, v124
	v_exp_f32_e32 v114, v109
	v_exp_f32_e32 v108, v125
	v_cvt_pk_bf16_f32 v9, v9, v104
	v_add_f32_e32 v109, v107, v105
	v_cvt_pk_bf16_f32 v97, v97, v106
	v_pk_add_f32 v[4:5], v[108:109], v[114:115]
	v_exp_f32_e32 v109, v110
	v_pk_add_f32 v[116:117], v[4:5], v[4:5] op_sel_hi:[0,1]
	v_exp_f32_e32 v115, v126
	v_exp_f32_e32 v116, v111
	v_exp_f32_e32 v110, v127
	v_cvt_pk_bf16_f32 v98, v107, v108
	v_add_f32_e32 v111, v115, v109
	v_cvt_pk_bf16_f32 v11, v109, v116
	v_pk_add_f32 v[4:5], v[110:111], v[116:117]
	s_nop 0
	v_add_f32_e32 v117, v4, v5
	v_cvt_pk_bf16_f32 v4, v3, v0
	v_add_u32_e32 v0, s78, v203
	v_cvt_pk_bf16_f32 v5, v7, v10
	v_cvt_pk_bf16_f32 v10, v105, v114
	v_cvt_pk_bf16_f32 v7, v99, v112
	v_cvt_pk_bf16_f32 v99, v115, v110
	v_add_u32_e32 v3, 0xc800, v0
	s_setprio 1
	ds_read_b64_tr_b16 v[214:215], v0 offset:51200
	ds_read_b64_tr_b16 v[216:217], v0 offset:53760
	ds_read_b64_tr_b16 v[218:219], v0 offset:51264
	ds_read_b64_tr_b16 v[220:221], v0 offset:53824
	ds_read_b64_tr_b16 v[222:223], v0 offset:51328
	ds_read_b64_tr_b16 v[224:225], v0 offset:53888
	ds_read_b64_tr_b16 v[226:227], v0 offset:51392
	ds_read_b64_tr_b16 v[228:229], v0 offset:53952
	ds_read_b64_tr_b16 v[230:231], v0 offset:56320
	ds_read_b64_tr_b16 v[232:233], v0 offset:58880
	ds_read_b64_tr_b16 v[234:235], v0 offset:56384
	ds_read_b64_tr_b16 v[236:237], v0 offset:58944
	ds_read_b64_tr_b16 v[238:239], v0 offset:56448
	ds_read_b64_tr_b16 v[240:241], v0 offset:59008
	s_waitcnt lgkmcnt(12)
	v_mfma_f32_32x32x16_bf16 v[64:79], v[4:7], v[214:217], v[64:79]
	v_add_f32_e32 v2, v2, v117
	ds_read_b64_tr_b16 v[214:215], v0 offset:56512
	ds_read_b64_tr_b16 v[216:217], v0 offset:59072
	s_waitcnt lgkmcnt(12)
	v_mfma_f32_32x32x16_bf16 v[48:63], v[4:7], v[218:221], v[48:63]
	ds_read_b64_tr_b16 v[218:219], v0 offset:61440
	ds_read_b64_tr_b16 v[220:221], v0 offset:64000
	s_waitcnt lgkmcnt(12)
	v_mfma_f32_32x32x16_bf16 v[32:47], v[4:7], v[222:225], v[32:47]
	ds_read_b64_tr_b16 v[222:223], v0 offset:61504
	ds_read_b64_tr_b16 v[224:225], v0 offset:64064
	s_waitcnt lgkmcnt(12)
	v_mfma_f32_32x32x16_bf16 v[16:31], v[4:7], v[226:229], v[16:31]
	ds_read_b64_tr_b16 v[226:227], v0 offset:61568
	ds_read_b64_tr_b16 v[228:229], v0 offset:64128
	s_waitcnt lgkmcnt(12)
	v_mfma_f32_32x32x16_bf16 v[64:79], v[8:11], v[230:233], v[64:79]
	ds_read_b64_tr_b16 v[230:231], v0 offset:61632
	ds_read_b64_tr_b16 v[232:233], v0 offset:64192
	s_waitcnt lgkmcnt(12)
	v_mfma_f32_32x32x16_bf16 v[48:63], v[8:11], v[234:237], v[48:63]
	ds_read_b64_tr_b16 v[234:235], v3 offset:15360
	ds_read_b64_tr_b16 v[236:237], v3 offset:17920
	s_waitcnt lgkmcnt(12)
	v_mfma_f32_32x32x16_bf16 v[32:47], v[8:11], v[238:241], v[32:47]
	ds_read_b64_tr_b16 v[238:239], v3 offset:15424
	ds_read_b64_tr_b16 v[240:241], v3 offset:17984
	s_waitcnt lgkmcnt(12)
	v_mfma_f32_32x32x16_bf16 v[16:31], v[8:11], v[214:217], v[16:31]
	ds_read_b64_tr_b16 v[214:215], v3 offset:15488
	ds_read_b64_tr_b16 v[216:217], v3 offset:18048
	s_waitcnt lgkmcnt(12)
	v_mfma_f32_32x32x16_bf16 v[64:79], v[12:15], v[218:221], v[64:79]
	ds_read_b64_tr_b16 v[218:219], v3 offset:15552
	ds_read_b64_tr_b16 v[220:221], v3 offset:18112
	s_waitcnt lgkmcnt(12)
	v_mfma_f32_32x32x16_bf16 v[48:63], v[12:15], v[222:225], v[48:63]
	s_waitcnt lgkmcnt(10)
	v_mfma_f32_32x32x16_bf16 v[32:47], v[12:15], v[226:229], v[32:47]
	s_waitcnt lgkmcnt(8)
	v_mfma_f32_32x32x16_bf16 v[16:31], v[12:15], v[230:233], v[16:31]
	s_waitcnt lgkmcnt(6)
	v_mfma_f32_32x32x16_bf16 v[64:79], v[96:99], v[234:237], v[64:79]
	s_waitcnt lgkmcnt(4)
	v_mfma_f32_32x32x16_bf16 v[48:63], v[96:99], v[238:241], v[48:63]
	s_waitcnt lgkmcnt(2)
	v_mfma_f32_32x32x16_bf16 v[32:47], v[96:99], v[214:217], v[32:47]
	s_waitcnt lgkmcnt(0)
	v_mfma_f32_32x32x16_bf16 v[16:31], v[96:99], v[218:221], v[16:31]
	s_setprio 0

; template <int DQK>
; __device__ __forceinline__ void attn_pass4(LAS unsigned char* lds, const bf16* Qp, int qpitch, const bf16* Kp, int kpitch, const bf16* Vp, int vpitch, int q0, f32x16 (&o)[4], float (&rl)[16]) {
;     ...
;             if (t > 0 && ATT_VIS(t - 1)) ATT_B(vprev);
.LBB0_2181:
	s_cmp_lg_u32 s12, 0
	s_cselect_b64 s[60:61], -1, 0
	s_cmp_eq_u32 s12, 0
	s_mov_b32 s24, 0
	s_cbranch_scc1 .LBB0_2185
	s_sub_i32 s24, s71, 64
	s_cmp_gt_i32 s24, s2
	s_cbranch_scc1 .LBB0_2184
	s_mulk_i32 s13, 0x5000
	v_add_u32_e32 v0, s13, v191
	v_add_u32_e32 v3, 0xc800, v0
	s_setprio 1
	ds_read_b64_tr_b16 v[214:215], v0 offset:51200
	ds_read_b64_tr_b16 v[216:217], v0 offset:53760
	ds_read_b64_tr_b16 v[218:219], v0 offset:51264
	ds_read_b64_tr_b16 v[220:221], v0 offset:53824
	ds_read_b64_tr_b16 v[222:223], v0 offset:51328
	ds_read_b64_tr_b16 v[224:225], v0 offset:53888
	ds_read_b64_tr_b16 v[226:227], v0 offset:51392
	ds_read_b64_tr_b16 v[228:229], v0 offset:53952
	ds_read_b64_tr_b16 v[230:231], v0 offset:56320
	ds_read_b64_tr_b16 v[232:233], v0 offset:58880
	ds_read_b64_tr_b16 v[234:235], v0 offset:56384
	ds_read_b64_tr_b16 v[236:237], v0 offset:58944
	ds_read_b64_tr_b16 v[238:239], v0 offset:56448
	ds_read_b64_tr_b16 v[240:241], v0 offset:59008
	s_waitcnt lgkmcnt(12)
	v_mfma_f32_32x32x16_bf16 v[64:79], v[108:111], v[214:217], v[64:79]
	ds_read_b64_tr_b16 v[214:215], v0 offset:56512
	ds_read_b64_tr_b16 v[216:217], v0 offset:59072
	s_waitcnt lgkmcnt(12)
	v_mfma_f32_32x32x16_bf16 v[48:63], v[108:111], v[218:221], v[48:63]
	ds_read_b64_tr_b16 v[218:219], v0 offset:61440
	ds_read_b64_tr_b16 v[220:221], v0 offset:64000
	s_waitcnt lgkmcnt(12)
	v_mfma_f32_32x32x16_bf16 v[32:47], v[108:111], v[222:225], v[32:47]
	ds_read_b64_tr_b16 v[222:223], v0 offset:61504
	ds_read_b64_tr_b16 v[224:225], v0 offset:64064
	s_waitcnt lgkmcnt(12)
	v_mfma_f32_32x32x16_bf16 v[16:31], v[108:111], v[226:229], v[16:31]
	ds_read_b64_tr_b16 v[226:227], v0 offset:61568
	ds_read_b64_tr_b16 v[228:229], v0 offset:64128
	s_waitcnt lgkmcnt(12)
	v_mfma_f32_32x32x16_bf16 v[64:79], v[104:107], v[230:233], v[64:79]
	ds_read_b64_tr_b16 v[230:231], v0 offset:61632
	ds_read_b64_tr_b16 v[232:233], v0 offset:64192
	s_waitcnt lgkmcnt(12)
	v_mfma_f32_32x32x16_bf16 v[48:63], v[104:107], v[234:237], v[48:63]
	ds_read_b64_tr_b16 v[234:235], v3 offset:15360
	ds_read_b64_tr_b16 v[236:237], v3 offset:17920
	s_waitcnt lgkmcnt(12)
	v_mfma_f32_32x32x16_bf16 v[32:47], v[104:107], v[238:241], v[32:47]
	ds_read_b64_tr_b16 v[238:239], v3 offset:15424
	ds_read_b64_tr_b16 v[240:241], v3 offset:17984
	s_waitcnt lgkmcnt(12)
	v_mfma_f32_32x32x16_bf16 v[16:31], v[104:107], v[214:217], v[16:31]
	ds_read_b64_tr_b16 v[214:215], v3 offset:15488
	ds_read_b64_tr_b16 v[216:217], v3 offset:18048
	s_waitcnt lgkmcnt(12)
	v_mfma_f32_32x32x16_bf16 v[64:79], v[100:103], v[218:221], v[64:79]
	ds_read_b64_tr_b16 v[218:219], v3 offset:15552
	ds_read_b64_tr_b16 v[220:221], v3 offset:18112
	s_waitcnt lgkmcnt(12)
	v_mfma_f32_32x32x16_bf16 v[48:63], v[100:103], v[222:225], v[48:63]
	s_waitcnt lgkmcnt(10)
	v_mfma_f32_32x32x16_bf16 v[32:47], v[100:103], v[226:229], v[32:47]
	s_waitcnt lgkmcnt(8)
	v_mfma_f32_32x32x16_bf16 v[16:31], v[100:103], v[230:233], v[16:31]
	s_waitcnt lgkmcnt(6)
	v_mfma_f32_32x32x16_bf16 v[64:79], v[96:99], v[234:237], v[64:79]
	s_waitcnt lgkmcnt(4)
	v_mfma_f32_32x32x16_bf16 v[48:63], v[96:99], v[238:241], v[48:63]
	s_waitcnt lgkmcnt(2)
	v_mfma_f32_32x32x16_bf16 v[32:47], v[96:99], v[214:217], v[32:47]
	s_waitcnt lgkmcnt(0)
	v_mfma_f32_32x32x16_bf16 v[16:31], v[96:99], v[218:221], v[16:31]
	s_setprio 0

; template <int DQK>
; __device__ __forceinline__ void attn_pass4(LAS unsigned char* lds, const bf16* Qp, int qpitch, const bf16* Kp, int kpitch, const bf16* Vp, int vpitch, int q0, f32x16 (&o)[4], float (&rl)[16]) {
;     ...
;             if (ATT_VIS(t)) ATT_A(t);
.LBB0_2185:
	s_cmp_gt_i32 s24, s2
	s_cbranch_scc1 .LBB0_2203
	s_bitcmp1_b32 s12, 0
	s_cselect_b32 s12, 0x6400, 0
	v_add_u32_e32 v0, s12, v200
	s_setprio 1
	ds_read_b128 v[214:217], v0
	ds_read_b128 v[218:221], v0 offset:32
	ds_read_b128 v[222:225], v0 offset:12800
	ds_read_b128 v[226:229], v0 offset:12832
	ds_read_b128 v[230:233], v0 offset:64
	ds_read_b128 v[234:237], v0 offset:12864
	ds_read_b128 v[238:241], v0 offset:96
	ds_read_b128 v[244:247], v0 offset:12896
	ds_read_b128 v[248:251], v0 offset:128
	s_waitcnt lgkmcnt(8)
	v_mfma_f32_32x32x16_bf16 v[96:111], v[214:217], v[128:131], v[80:95]
	ds_read_b128 v[214:217], v0 offset:12928
	s_waitcnt lgkmcnt(8)
	v_mfma_f32_32x32x16_bf16 v[96:111], v[218:221], v[132:135], v[96:111]
	ds_read_b128 v[218:221], v0 offset:160
	s_waitcnt lgkmcnt(8)
	v_mfma_f32_32x32x16_bf16 v[112:127], v[222:225], v[128:131], v[80:95]
	ds_read_b128 v[222:225], v0 offset:12960
	s_waitcnt lgkmcnt(8)
	v_mfma_f32_32x32x16_bf16 v[112:127], v[226:229], v[132:135], v[112:127]
	ds_read_b128 v[226:229], v0 offset:192
	s_waitcnt lgkmcnt(8)
	v_mfma_f32_32x32x16_bf16 v[96:111], v[230:233], v[136:139], v[96:111]
	ds_read_b128 v[230:233], v0 offset:12992
	s_waitcnt lgkmcnt(8)
	v_mfma_f32_32x32x16_bf16 v[112:127], v[234:237], v[136:139], v[112:127]
	ds_read_b128 v[234:237], v0 offset:224
	s_waitcnt lgkmcnt(8)
	v_mfma_f32_32x32x16_bf16 v[96:111], v[238:241], v[140:143], v[96:111]
	ds_read_b128 v[238:241], v0 offset:13024
	s_waitcnt lgkmcnt(8)
	v_mfma_f32_32x32x16_bf16 v[112:127], v[244:247], v[140:143], v[112:127]
	ds_read_b128 v[244:247], v0 offset:256
	s_waitcnt lgkmcnt(8)
	v_mfma_f32_32x32x16_bf16 v[96:111], v[248:251], v[144:147], v[96:111]
	ds_read_b128 v[248:251], v0 offset:13056
	s_waitcnt lgkmcnt(8)
	v_mfma_f32_32x32x16_bf16 v[112:127], v[214:217], v[144:147], v[112:127]
	ds_read_b128 v[214:217], v0 offset:288
	s_waitcnt lgkmcnt(8)
	v_mfma_f32_32x32x16_bf16 v[96:111], v[218:221], v[148:151], v[96:111]
	ds_read_b128 v[218:221], v0 offset:13088
	s_waitcnt lgkmcnt(8)
	v_mfma_f32_32x32x16_bf16 v[112:127], v[222:225], v[148:151], v[112:127]
	ds_read_b128 v[222:225], v0 offset:320
	s_waitcnt lgkmcnt(8)
	v_mfma_f32_32x32x16_bf16 v[96:111], v[226:229], v[152:155], v[96:111]
	ds_read_b128 v[226:229], v0 offset:13120
	s_waitcnt lgkmcnt(8)
	v_mfma_f32_32x32x16_bf16 v[112:127], v[230:233], v[152:155], v[112:127]
	ds_read_b128 v[230:233], v0 offset:352
	s_waitcnt lgkmcnt(8)
	v_mfma_f32_32x32x16_bf16 v[96:111], v[234:237], v[156:159], v[96:111]
	ds_read_b128 v[234:237], v0 offset:13152
	s_waitcnt lgkmcnt(8)
	v_mfma_f32_32x32x16_bf16 v[112:127], v[238:241], v[156:159], v[112:127]
	s_waitcnt lgkmcnt(7)
	v_mfma_f32_32x32x16_bf16 v[96:111], v[244:247], v[160:163], v[96:111]
	s_waitcnt lgkmcnt(6)
	v_mfma_f32_32x32x16_bf16 v[112:127], v[248:251], v[160:163], v[112:127]
	s_waitcnt lgkmcnt(5)
	v_mfma_f32_32x32x16_bf16 v[96:111], v[214:217], v[164:167], v[96:111]
	s_waitcnt lgkmcnt(4)
	v_mfma_f32_32x32x16_bf16 v[112:127], v[218:221], v[164:167], v[112:127]
	s_waitcnt lgkmcnt(3)
	v_mfma_f32_32x32x16_bf16 v[96:111], v[222:225], v[168:171], v[96:111]
	s_waitcnt lgkmcnt(2)
	v_mfma_f32_32x32x16_bf16 v[112:127], v[226:229], v[168:171], v[112:127]
	s_waitcnt lgkmcnt(1)
	v_mfma_f32_32x32x16_bf16 v[96:111], v[230:233], v[172:175], v[96:111]
	s_waitcnt lgkmcnt(0)
	v_mfma_f32_32x32x16_bf16 v[112:127], v[234:237], v[172:175], v[112:127]
	s_setprio 0
	s_or_b32 s12, s24, 63
	s_cmp_le_i32 s12, s68
	s_cbranch_scc1 .LBB0_2188
	v_or_b32_e32 v0, s24, v201
	v_or_b32_e32 v3, 32, v0
	v_cmp_le_i32_e32 vcc, v3, v197
	v_or_b32_e32 v3, 33, v0
	s_nop 3
	v_cndmask_b32_e32 v112, v194, v112, vcc
	v_cmp_lt_i32_e32 vcc, v0, v197
	s_nop 1
	v_cndmask_b32_e32 v97, v194, v97, vcc
	v_cmp_le_i32_e32 vcc, v0, v197
	s_nop 1
	v_cndmask_b32_e32 v96, v194, v96, vcc
	v_cmp_le_i32_e32 vcc, v3, v197
	v_or_b32_e32 v3, 2, v0
	s_nop 0
	v_cndmask_b32_e32 v113, v194, v113, vcc
	v_cmp_le_i32_e32 vcc, v3, v197
	v_or_b32_e32 v3, 34, v0
	s_nop 0
	v_cndmask_b32_e32 v98, v194, v98, vcc
	v_cmp_le_i32_e32 vcc, v3, v197
	v_or_b32_e32 v3, 3, v0
	s_nop 0
	v_cndmask_b32_e32 v114, v194, v114, vcc
	v_cmp_le_i32_e32 vcc, v3, v197
	v_or_b32_e32 v3, 35, v0
	s_nop 0
	v_cndmask_b32_e32 v99, v194, v99, vcc
	v_cmp_le_i32_e32 vcc, v3, v197
	v_or_b32_e32 v3, 8, v0
	s_nop 0
	v_cndmask_b32_e32 v115, v194, v115, vcc
	v_cmp_le_i32_e32 vcc, v3, v197
	v_or_b32_e32 v3, 40, v0
	s_nop 0
	v_cndmask_b32_e32 v100, v194, v100, vcc
	v_cmp_le_i32_e32 vcc, v3, v197
	v_or_b32_e32 v3, 9, v0
	s_nop 0
	v_cndmask_b32_e32 v116, v194, v116, vcc
	v_cmp_le_i32_e32 vcc, v3, v197
	v_or_b32_e32 v3, 41, v0
	s_nop 0
	v_cndmask_b32_e32 v101, v194, v101, vcc
	v_cmp_le_i32_e32 vcc, v3, v197
	v_or_b32_e32 v3, 10, v0
	s_nop 0
	v_cndmask_b32_e32 v117, v194, v117, vcc
	v_cmp_le_i32_e32 vcc, v3, v197
	v_or_b32_e32 v3, 42, v0
	s_nop 0
	v_cndmask_b32_e32 v102, v194, v102, vcc
	v_cmp_le_i32_e32 vcc, v3, v197
	v_or_b32_e32 v3, 11, v0
	s_nop 0
	v_cndmask_b32_e32 v118, v194, v118, vcc
	v_cmp_le_i32_e32 vcc, v3, v197
	v_or_b32_e32 v3, 43, v0
	s_nop 0
	v_cndmask_b32_e32 v103, v194, v103, vcc
	v_cmp_le_i32_e32 vcc, v3, v197
	v_or_b32_e32 v3, 16, v0
	s_nop 0
	v_cndmask_b32_e32 v119, v194, v119, vcc
	v_cmp_le_i32_e32 vcc, v3, v197
	v_or_b32_e32 v3, 48, v0
	s_nop 0
	v_cndmask_b32_e32 v104, v194, v104, vcc
	v_cmp_le_i32_e32 vcc, v3, v197
	v_or_b32_e32 v3, 17, v0
	s_nop 0
	v_cndmask_b32_e32 v120, v194, v120, vcc
	v_cmp_le_i32_e32 vcc, v3, v197
	v_or_b32_e32 v3, 49, v0
	s_nop 0
	v_cndmask_b32_e32 v105, v194, v105, vcc
	v_cmp_le_i32_e32 vcc, v3, v197
	v_or_b32_e32 v3, 18, v0
	s_nop 0
	v_cndmask_b32_e32 v121, v194, v121, vcc
	v_cmp_le_i32_e32 vcc, v3, v197
	v_or_b32_e32 v3, 50, v0
	s_nop 0
	v_cndmask_b32_e32 v106, v194, v106, vcc
	v_cmp_le_i32_e32 vcc, v3, v197
	v_or_b32_e32 v3, 19, v0
	s_nop 0
	v_cndmask_b32_e32 v122, v194, v122, vcc
	v_cmp_le_i32_e32 vcc, v3, v197
	v_or_b32_e32 v3, 51, v0
	s_nop 0
	v_cndmask_b32_e32 v107, v194, v107, vcc
	v_cmp_le_i32_e32 vcc, v3, v197
	v_or_b32_e32 v3, 24, v0
	s_nop 0
	v_cndmask_b32_e32 v123, v194, v123, vcc
	v_cmp_le_i32_e32 vcc, v3, v197
	v_or_b32_e32 v3, 56, v0
	s_nop 0
	v_cndmask_b32_e32 v108, v194, v108, vcc
	v_cmp_le_i32_e32 vcc, v3, v197
	v_or_b32_e32 v3, 25, v0
	s_nop 0
	v_cndmask_b32_e32 v124, v194, v124, vcc
	v_cmp_le_i32_e32 vcc, v3, v197
	v_or_b32_e32 v3, 57, v0
	s_nop 0
	v_cndmask_b32_e32 v109, v194, v109, vcc
	v_cmp_le_i32_e32 vcc, v3, v197
	v_or_b32_e32 v3, 26, v0
	s_nop 0
	v_cndmask_b32_e32 v125, v194, v125, vcc
	v_cmp_le_i32_e32 vcc, v3, v197
	v_or_b32_e32 v3, 58, v0
	s_nop 0
	v_cndmask_b32_e32 v110, v194, v110, vcc
	v_cmp_le_i32_e32 vcc, v3, v197
	v_or_b32_e32 v3, 27, v0
	v_or_b32_e32 v0, 59, v0
	v_cndmask_b32_e32 v126, v194, v126, vcc
	v_cmp_le_i32_e32 vcc, v3, v197
	s_nop 1
	v_cndmask_b32_e32 v111, v194, v111, vcc
	v_cmp_le_i32_e32 vcc, v0, v197
	s_nop 1
	v_cndmask_b32_e32 v127, v194, v127, vcc

; template <int DQK>
; __device__ __forceinline__ void attn_pass4(LAS unsigned char* lds, const bf16* Qp, int qpitch, const bf16* Kp, int kpitch, const bf16* Vp, int vpitch, int q0, f32x16 (&o)[4], float (&rl)[16]) {
;     ...
;         if (ATT_VIS(NT - 1)) ATT_B(vprev);
.LBB0_2205:
	s_cmp_gt_i32 s67, 5
	s_cbranch_scc0 .LBB0_2207
	s_mul_i32 s2, s73, 0x5000
	s_add_i32 s2, s2, 0
	v_add_u32_e32 v0, s2, v190
	v_add3_u32 v0, v0, v198, v199
	v_add_u32_e32 v3, 0xc800, v0
	s_setprio 1
	ds_read_b64_tr_b16 v[214:215], v0 offset:51200
	ds_read_b64_tr_b16 v[216:217], v0 offset:53760
	ds_read_b64_tr_b16 v[218:219], v0 offset:51264
	ds_read_b64_tr_b16 v[220:221], v0 offset:53824
	ds_read_b64_tr_b16 v[222:223], v0 offset:51328
	ds_read_b64_tr_b16 v[224:225], v0 offset:53888
	ds_read_b64_tr_b16 v[226:227], v0 offset:51392
	ds_read_b64_tr_b16 v[228:229], v0 offset:53952
	ds_read_b64_tr_b16 v[230:231], v0 offset:56320
	ds_read_b64_tr_b16 v[232:233], v0 offset:58880
	ds_read_b64_tr_b16 v[234:235], v0 offset:56384
	ds_read_b64_tr_b16 v[236:237], v0 offset:58944
	ds_read_b64_tr_b16 v[238:239], v0 offset:56448
	ds_read_b64_tr_b16 v[240:241], v0 offset:59008
	s_waitcnt lgkmcnt(12)
	v_mfma_f32_32x32x16_bf16 v[64:79], v[108:111], v[214:217], v[64:79]
	ds_read_b64_tr_b16 v[214:215], v0 offset:56512
	ds_read_b64_tr_b16 v[216:217], v0 offset:59072
	s_waitcnt lgkmcnt(12)
	v_mfma_f32_32x32x16_bf16 v[48:63], v[108:111], v[218:221], v[48:63]
	ds_read_b64_tr_b16 v[218:219], v0 offset:61440
	ds_read_b64_tr_b16 v[220:221], v0 offset:64000
	s_waitcnt lgkmcnt(12)
	v_mfma_f32_32x32x16_bf16 v[32:47], v[108:111], v[222:225], v[32:47]
	ds_read_b64_tr_b16 v[222:223], v0 offset:61504
	ds_read_b64_tr_b16 v[224:225], v0 offset:64064
	s_waitcnt lgkmcnt(12)
	v_mfma_f32_32x32x16_bf16 v[16:31], v[108:111], v[226:229], v[16:31]
	ds_read_b64_tr_b16 v[226:227], v0 offset:61568
	ds_read_b64_tr_b16 v[228:229], v0 offset:64128
	s_waitcnt lgkmcnt(12)
	v_mfma_f32_32x32x16_bf16 v[64:79], v[104:107], v[230:233], v[64:79]
	ds_read_b64_tr_b16 v[230:231], v0 offset:61632
	ds_read_b64_tr_b16 v[232:233], v0 offset:64192
	s_waitcnt lgkmcnt(12)
	v_mfma_f32_32x32x16_bf16 v[48:63], v[104:107], v[234:237], v[48:63]
	ds_read_b64_tr_b16 v[234:235], v3 offset:15360
	ds_read_b64_tr_b16 v[236:237], v3 offset:17920
	s_waitcnt lgkmcnt(12)
	v_mfma_f32_32x32x16_bf16 v[32:47], v[104:107], v[238:241], v[32:47]
	ds_read_b64_tr_b16 v[238:239], v3 offset:15424
	ds_read_b64_tr_b16 v[240:241], v3 offset:17984
	s_waitcnt lgkmcnt(12)
	v_mfma_f32_32x32x16_bf16 v[16:31], v[104:107], v[214:217], v[16:31]
	ds_read_b64_tr_b16 v[214:215], v3 offset:15488
	ds_read_b64_tr_b16 v[216:217], v3 offset:18048
	s_waitcnt lgkmcnt(12)
	v_mfma_f32_32x32x16_bf16 v[64:79], v[100:103], v[218:221], v[64:79]
	ds_read_b64_tr_b16 v[218:219], v3 offset:15552
	ds_read_b64_tr_b16 v[220:221], v3 offset:18112
	s_waitcnt lgkmcnt(12)
	v_mfma_f32_32x32x16_bf16 v[48:63], v[100:103], v[222:225], v[48:63]
	s_waitcnt lgkmcnt(10)
	v_mfma_f32_32x32x16_bf16 v[32:47], v[100:103], v[226:229], v[32:47]
	s_waitcnt lgkmcnt(8)
	v_mfma_f32_32x32x16_bf16 v[16:31], v[100:103], v[230:233], v[16:31]
	s_waitcnt lgkmcnt(6)
	v_mfma_f32_32x32x16_bf16 v[64:79], v[96:99], v[234:237], v[64:79]
	s_waitcnt lgkmcnt(4)
	v_mfma_f32_32x32x16_bf16 v[48:63], v[96:99], v[238:241], v[48:63]
	s_waitcnt lgkmcnt(2)
	v_mfma_f32_32x32x16_bf16 v[32:47], v[96:99], v[214:217], v[32:47]
	s_waitcnt lgkmcnt(0)
	v_mfma_f32_32x32x16_bf16 v[16:31], v[96:99], v[218:221], v[16:31]
	s_setprio 0
